# scan waves: operand reads issued two steps ahead into their own buffer right after the last consumer (gen_scan7.py), on v192
# baseline (speedup 1.0000x reference)
.LBB0_390:
	s_and_b32 s3, s2, 1
	s_mul_i32 s8, s3, 0x5000
	v_add_u32_e32 v2, s8, v136
	s_mul_i32 s8, s2, 0xab
	s_bfe_u32 s8, s8, 0x70009
	s_mul_i32 s8, s8, 3
	s_sub_i32 s8, s2, s8
	s_and_b32 s8, s8, 0xff
	s_mulk_i32 s8, 0x1100
	v_add_u32_e32 v3, s8, v137
	v_lshl_add_u32 v1, s3, 12, v137
	ds_read_b128 v[176:179], v2 offset:4096
	ds_read_b128 v[180:183], v2 offset:4112
	ds_read_b128 v[200:203], v2 offset:12288
	ds_read_b128 v[204:207], v2 offset:12304
	ds_read_b64 v[216:217], v3 offset:40960
	ds_read_b128 v[184:187], v2 offset:0
	ds_read_b128 v[188:191], v2 offset:16
	ds_read_b128 v[192:195], v2 offset:8192
	ds_read_b128 v[196:199], v2 offset:8208
	ds_read_b128 v[208:211], v2 offset:16384
	ds_read_b128 v[212:215], v2 offset:16400
	ds_read_b128 v[4:7], v2 offset:4352
	ds_read_b128 v[8:11], v2 offset:4368
	ds_read_b128 v[40:43], v2 offset:12544
	ds_read_b128 v[44:47], v2 offset:12560
	ds_read_b64 v[26:27], v3 offset:41216
	ds_read_b128 v[12:15], v2 offset:256
	ds_read_b128 v[28:31], v2 offset:272
	ds_read_b128 v[32:35], v2 offset:8448
	ds_read_b128 v[36:39], v2 offset:8464
	s_waitcnt lgkmcnt(15)
	v_pk_mul_f32 v[164:165], v[72:73], v[176:177]
	v_pk_mul_f32 v[166:167], v[80:81], v[176:177]
	v_pk_fma_f32 v[164:165], v[74:75], v[178:179], v[164:165]
	v_pk_fma_f32 v[166:167], v[82:83], v[178:179], v[166:167]
	s_waitcnt lgkmcnt(15)
	v_pk_fma_f32 v[164:165], v[76:77], v[180:181], v[164:165]
	v_pk_fma_f32 v[166:167], v[84:85], v[180:181], v[166:167]
	v_pk_fma_f32 v[164:165], v[78:79], v[182:183], v[164:165]
	v_pk_fma_f32 v[166:167], v[86:87], v[182:183], v[166:167]
	s_waitcnt lgkmcnt(15)
	v_pk_mul_f32 v[218:219], v[216:217], v[200:201] op_sel_hi:[0,1]
	v_pk_mul_f32 v[226:227], v[216:217], v[200:201] op_sel:[1,0]
	ds_read_b128 v[176:179], v2 offset:4608
	v_pk_mul_f32 v[220:221], v[216:217], v[202:203] op_sel_hi:[0,1]
	v_pk_mul_f32 v[228:229], v[216:217], v[202:203] op_sel:[1,0]
	ds_read_b128 v[180:183], v2 offset:4624
	v_pk_mul_f32 v[222:223], v[216:217], v[204:205] op_sel_hi:[0,1]
	v_pk_mul_f32 v[230:231], v[216:217], v[204:205] op_sel:[1,0]
	ds_read_b128 v[48:51], v2 offset:16640
	v_pk_mul_f32 v[224:225], v[216:217], v[206:207] op_sel_hi:[0,1]
	v_pk_mul_f32 v[234:235], v[216:217], v[206:207] op_sel:[1,0]
	ds_read_b128 v[52:55], v2 offset:16656
	v_add_f32_e32 v172, v164, v165
	v_add_f32_e32 v174, v166, v167
	ds_read_b128 v[200:203], v2 offset:12800
	s_waitcnt lgkmcnt(15)
	v_pk_fma_f32 v[218:219], v[72:73], v[184:185], v[218:219]
	v_pk_fma_f32 v[226:227], v[80:81], v[184:185], v[226:227]
	ds_read_b128 v[204:207], v2 offset:12816
	v_pk_fma_f32 v[220:221], v[74:75], v[186:187], v[220:221]
	v_pk_fma_f32 v[228:229], v[82:83], v[186:187], v[228:229]
	ds_read_b64 v[216:217], v3 offset:41472
	v_add_f32_dpp v172, v172, v172 quad_perm:[1,0,3,2] row_mask:0xf bank_mask:0xf bound_ctrl:1
	v_add_f32_dpp v174, v174, v174 quad_perm:[1,0,3,2] row_mask:0xf bank_mask:0xf bound_ctrl:1
	s_waitcnt lgkmcnt(15)
	v_pk_fma_f32 v[222:223], v[76:77], v[188:189], v[222:223]
	v_pk_fma_f32 v[230:231], v[84:85], v[188:189], v[230:231]
	v_pk_fma_f32 v[224:225], v[78:79], v[190:191], v[224:225]
	v_pk_fma_f32 v[234:235], v[86:87], v[190:191], v[234:235]
	v_add_f32_dpp v172, v172, v172 quad_perm:[2,3,0,1] row_mask:0xf bank_mask:0xf bound_ctrl:1
	v_add_f32_dpp v174, v174, v174 quad_perm:[2,3,0,1] row_mask:0xf bank_mask:0xf bound_ctrl:1
	ds_read_b128 v[184:187], v2 offset:512
	v_add_f32_dpp v172, v172, v172 row_half_mirror row_mask:0xf bank_mask:0xf bound_ctrl:1
	v_add_f32_dpp v174, v174, v174 row_half_mirror row_mask:0xf bank_mask:0xf bound_ctrl:1
	ds_read_b128 v[188:191], v2 offset:528
	s_waitcnt lgkmcnt(15)
	v_pk_fma_f32 v[72:73], v[192:193], v[172:173], v[218:219] op_sel_hi:[1,0,1]
	v_pk_fma_f32 v[80:81], v[192:193], v[174:175], v[226:227] op_sel_hi:[1,0,1]
	v_pk_fma_f32 v[74:75], v[194:195], v[172:173], v[220:221] op_sel_hi:[1,0,1]
	v_pk_fma_f32 v[82:83], v[194:195], v[174:175], v[228:229] op_sel_hi:[1,0,1]
	s_waitcnt lgkmcnt(15)
	v_pk_fma_f32 v[76:77], v[196:197], v[172:173], v[222:223] op_sel_hi:[1,0,1]
	v_pk_fma_f32 v[84:85], v[196:197], v[174:175], v[230:231] op_sel_hi:[1,0,1]
	v_pk_fma_f32 v[78:79], v[198:199], v[172:173], v[224:225] op_sel_hi:[1,0,1]
	v_pk_fma_f32 v[86:87], v[198:199], v[174:175], v[234:235] op_sel_hi:[1,0,1]
	ds_read_b128 v[192:195], v2 offset:8704
	ds_read_b128 v[196:199], v2 offset:8720
	s_waitcnt lgkmcnt(15)
	v_pk_mul_f32 v[164:165], v[72:73], v[4:5]
	v_pk_mul_f32 v[166:167], v[80:81], v[4:5]
	v_pk_mul_f32 v[168:169], v[72:73], v[208:209]
	v_pk_mul_f32 v[170:171], v[80:81], v[208:209]
	v_pk_fma_f32 v[164:165], v[74:75], v[6:7], v[164:165]
	v_pk_fma_f32 v[166:167], v[82:83], v[6:7], v[166:167]
	v_pk_fma_f32 v[168:169], v[74:75], v[210:211], v[168:169]
	v_pk_fma_f32 v[170:171], v[82:83], v[210:211], v[170:171]
	s_waitcnt lgkmcnt(15)
	v_pk_fma_f32 v[164:165], v[76:77], v[8:9], v[164:165]
	v_pk_fma_f32 v[166:167], v[84:85], v[8:9], v[166:167]
	v_pk_fma_f32 v[168:169], v[76:77], v[212:213], v[168:169]
	v_pk_fma_f32 v[170:171], v[84:85], v[212:213], v[170:171]
	v_pk_fma_f32 v[164:165], v[78:79], v[10:11], v[164:165]
	v_pk_fma_f32 v[166:167], v[86:87], v[10:11], v[166:167]
	v_pk_fma_f32 v[168:169], v[78:79], v[214:215], v[168:169]
	v_pk_fma_f32 v[170:171], v[86:87], v[214:215], v[170:171]
	s_waitcnt lgkmcnt(15)
	v_pk_mul_f32 v[218:219], v[26:27], v[40:41] op_sel_hi:[0,1]
	v_pk_mul_f32 v[226:227], v[26:27], v[40:41] op_sel:[1,0]
	ds_read_b128 v[4:7], v2 offset:4864
	v_pk_mul_f32 v[220:221], v[26:27], v[42:43] op_sel_hi:[0,1]
	v_pk_mul_f32 v[228:229], v[26:27], v[42:43] op_sel:[1,0]
	ds_read_b128 v[8:11], v2 offset:4880
	v_pk_mul_f32 v[222:223], v[26:27], v[44:45] op_sel_hi:[0,1]
	v_pk_mul_f32 v[230:231], v[26:27], v[44:45] op_sel:[1,0]
	ds_read_b128 v[208:211], v2 offset:16896
	v_pk_mul_f32 v[224:225], v[26:27], v[46:47] op_sel_hi:[0,1]
	v_pk_mul_f32 v[234:235], v[26:27], v[46:47] op_sel:[1,0]
	ds_read_b128 v[212:215], v2 offset:16912
	v_add_f32_e32 v172, v164, v165
	v_add_f32_e32 v174, v166, v167
	ds_read_b128 v[40:43], v2 offset:13056
	v_add_f32_e32 v160, v168, v169
	v_add_f32_e32 v161, v170, v171
	ds_read_b128 v[44:47], v2 offset:13072
	s_waitcnt lgkmcnt(15)
	v_pk_fma_f32 v[218:219], v[72:73], v[12:13], v[218:219]
	v_pk_fma_f32 v[226:227], v[80:81], v[12:13], v[226:227]
	ds_read_b64 v[26:27], v3 offset:41728
	v_pk_fma_f32 v[220:221], v[74:75], v[14:15], v[220:221]
	v_pk_fma_f32 v[228:229], v[82:83], v[14:15], v[228:229]
	v_add_f32_dpp v172, v172, v172 quad_perm:[1,0,3,2] row_mask:0xf bank_mask:0xf bound_ctrl:1
	v_add_f32_dpp v174, v174, v174 quad_perm:[1,0,3,2] row_mask:0xf bank_mask:0xf bound_ctrl:1
	v_add_f32_dpp v160, v160, v160 quad_perm:[1,0,3,2] row_mask:0xf bank_mask:0xf bound_ctrl:1
	v_add_f32_dpp v161, v161, v161 quad_perm:[1,0,3,2] row_mask:0xf bank_mask:0xf bound_ctrl:1
	s_waitcnt lgkmcnt(15)
	v_pk_fma_f32 v[222:223], v[76:77], v[28:29], v[222:223]
	v_pk_fma_f32 v[230:231], v[84:85], v[28:29], v[230:231]
	v_pk_fma_f32 v[224:225], v[78:79], v[30:31], v[224:225]
	v_pk_fma_f32 v[234:235], v[86:87], v[30:31], v[234:235]
	v_add_f32_dpp v172, v172, v172 quad_perm:[2,3,0,1] row_mask:0xf bank_mask:0xf bound_ctrl:1
	v_add_f32_dpp v174, v174, v174 quad_perm:[2,3,0,1] row_mask:0xf bank_mask:0xf bound_ctrl:1
	ds_read_b128 v[12:15], v2 offset:768
	v_add_f32_dpp v160, v160, v160 quad_perm:[2,3,0,1] row_mask:0xf bank_mask:0xf bound_ctrl:1
	v_add_f32_dpp v161, v161, v161 quad_perm:[2,3,0,1] row_mask:0xf bank_mask:0xf bound_ctrl:1
	ds_read_b128 v[28:31], v2 offset:784
	v_add_f32_dpp v172, v172, v172 row_half_mirror row_mask:0xf bank_mask:0xf bound_ctrl:1
	v_add_f32_dpp v174, v174, v174 row_half_mirror row_mask:0xf bank_mask:0xf bound_ctrl:1
	v_add_f32_dpp v160, v160, v160 row_half_mirror row_mask:0xf bank_mask:0xf bound_ctrl:1
	v_add_f32_dpp v161, v161, v161 row_half_mirror row_mask:0xf bank_mask:0xf bound_ctrl:1
	s_waitcnt lgkmcnt(15)
	v_pk_fma_f32 v[72:73], v[32:33], v[172:173], v[218:219] op_sel_hi:[1,0,1]
	v_pk_fma_f32 v[80:81], v[32:33], v[174:175], v[226:227] op_sel_hi:[1,0,1]
	v_pk_fma_f32 v[74:75], v[34:35], v[172:173], v[220:221] op_sel_hi:[1,0,1]
	v_pk_fma_f32 v[82:83], v[34:35], v[174:175], v[228:229] op_sel_hi:[1,0,1]
	s_waitcnt lgkmcnt(15)
	v_pk_fma_f32 v[76:77], v[36:37], v[172:173], v[222:223] op_sel_hi:[1,0,1]
	v_pk_fma_f32 v[84:85], v[36:37], v[174:175], v[230:231] op_sel_hi:[1,0,1]
	v_pk_fma_f32 v[78:79], v[38:39], v[172:173], v[224:225] op_sel_hi:[1,0,1]
	v_pk_fma_f32 v[86:87], v[38:39], v[174:175], v[234:235] op_sel_hi:[1,0,1]
	ds_read_b128 v[32:35], v2 offset:8960
	ds_read_b128 v[36:39], v2 offset:8976
	ds_write_b64 v1, v[160:161] offset:54016
	s_waitcnt lgkmcnt(15)
	v_pk_mul_f32 v[164:165], v[72:73], v[176:177]
	v_pk_mul_f32 v[166:167], v[80:81], v[176:177]
	s_waitcnt lgkmcnt(15)
	v_pk_mul_f32 v[168:169], v[72:73], v[48:49]
	v_pk_mul_f32 v[170:171], v[80:81], v[48:49]
	v_pk_fma_f32 v[164:165], v[74:75], v[178:179], v[164:165]
	v_pk_fma_f32 v[166:167], v[82:83], v[178:179], v[166:167]
	v_pk_fma_f32 v[168:169], v[74:75], v[50:51], v[168:169]
	v_pk_fma_f32 v[170:171], v[82:83], v[50:51], v[170:171]
	v_pk_fma_f32 v[164:165], v[76:77], v[180:181], v[164:165]
	v_pk_fma_f32 v[166:167], v[84:85], v[180:181], v[166:167]
	s_waitcnt lgkmcnt(15)
	v_pk_fma_f32 v[168:169], v[76:77], v[52:53], v[168:169]
	v_pk_fma_f32 v[170:171], v[84:85], v[52:53], v[170:171]
	v_pk_fma_f32 v[164:165], v[78:79], v[182:183], v[164:165]
	v_pk_fma_f32 v[166:167], v[86:87], v[182:183], v[166:167]
	v_pk_fma_f32 v[168:169], v[78:79], v[54:55], v[168:169]
	v_pk_fma_f32 v[170:171], v[86:87], v[54:55], v[170:171]
	s_waitcnt lgkmcnt(15)
	v_pk_mul_f32 v[218:219], v[216:217], v[200:201] op_sel_hi:[0,1]
	v_pk_mul_f32 v[226:227], v[216:217], v[200:201] op_sel:[1,0]
	ds_read_b128 v[176:179], v2 offset:5120
	v_pk_mul_f32 v[220:221], v[216:217], v[202:203] op_sel_hi:[0,1]
	v_pk_mul_f32 v[228:229], v[216:217], v[202:203] op_sel:[1,0]
	ds_read_b128 v[180:183], v2 offset:5136
	v_pk_mul_f32 v[222:223], v[216:217], v[204:205] op_sel_hi:[0,1]
	v_pk_mul_f32 v[230:231], v[216:217], v[204:205] op_sel:[1,0]
	ds_read_b128 v[48:51], v2 offset:17152
	v_pk_mul_f32 v[224:225], v[216:217], v[206:207] op_sel_hi:[0,1]
	v_pk_mul_f32 v[234:235], v[216:217], v[206:207] op_sel:[1,0]
	ds_read_b128 v[52:55], v2 offset:17168
	v_add_f32_e32 v172, v164, v165
	v_add_f32_e32 v174, v166, v167
	ds_read_b128 v[200:203], v2 offset:13312
	v_add_f32_e32 v160, v168, v169
	v_add_f32_e32 v161, v170, v171
	ds_read_b128 v[204:207], v2 offset:13328
	s_waitcnt lgkmcnt(15)
	v_pk_fma_f32 v[218:219], v[72:73], v[184:185], v[218:219]
	v_pk_fma_f32 v[226:227], v[80:81], v[184:185], v[226:227]
	ds_read_b64 v[216:217], v3 offset:41984
	v_pk_fma_f32 v[220:221], v[74:75], v[186:187], v[220:221]
	v_pk_fma_f32 v[228:229], v[82:83], v[186:187], v[228:229]
	v_add_f32_dpp v172, v172, v172 quad_perm:[1,0,3,2] row_mask:0xf bank_mask:0xf bound_ctrl:1
	v_add_f32_dpp v174, v174, v174 quad_perm:[1,0,3,2] row_mask:0xf bank_mask:0xf bound_ctrl:1
	v_add_f32_dpp v160, v160, v160 quad_perm:[1,0,3,2] row_mask:0xf bank_mask:0xf bound_ctrl:1
	v_add_f32_dpp v161, v161, v161 quad_perm:[1,0,3,2] row_mask:0xf bank_mask:0xf bound_ctrl:1
	s_waitcnt lgkmcnt(15)
	v_pk_fma_f32 v[222:223], v[76:77], v[188:189], v[222:223]
	v_pk_fma_f32 v[230:231], v[84:85], v[188:189], v[230:231]
	v_pk_fma_f32 v[224:225], v[78:79], v[190:191], v[224:225]
	v_pk_fma_f32 v[234:235], v[86:87], v[190:191], v[234:235]
	v_add_f32_dpp v172, v172, v172 quad_perm:[2,3,0,1] row_mask:0xf bank_mask:0xf bound_ctrl:1
	v_add_f32_dpp v174, v174, v174 quad_perm:[2,3,0,1] row_mask:0xf bank_mask:0xf bound_ctrl:1
	ds_read_b128 v[184:187], v2 offset:1024
	v_add_f32_dpp v160, v160, v160 quad_perm:[2,3,0,1] row_mask:0xf bank_mask:0xf bound_ctrl:1
	v_add_f32_dpp v161, v161, v161 quad_perm:[2,3,0,1] row_mask:0xf bank_mask:0xf bound_ctrl:1
	ds_read_b128 v[188:191], v2 offset:1040
	v_add_f32_dpp v172, v172, v172 row_half_mirror row_mask:0xf bank_mask:0xf bound_ctrl:1
	v_add_f32_dpp v174, v174, v174 row_half_mirror row_mask:0xf bank_mask:0xf bound_ctrl:1
	v_add_f32_dpp v160, v160, v160 row_half_mirror row_mask:0xf bank_mask:0xf bound_ctrl:1
	v_add_f32_dpp v161, v161, v161 row_half_mirror row_mask:0xf bank_mask:0xf bound_ctrl:1
	s_waitcnt lgkmcnt(15)
	v_pk_fma_f32 v[72:73], v[192:193], v[172:173], v[218:219] op_sel_hi:[1,0,1]
	v_pk_fma_f32 v[80:81], v[192:193], v[174:175], v[226:227] op_sel_hi:[1,0,1]
	v_pk_fma_f32 v[74:75], v[194:195], v[172:173], v[220:221] op_sel_hi:[1,0,1]
	v_pk_fma_f32 v[82:83], v[194:195], v[174:175], v[228:229] op_sel_hi:[1,0,1]
	s_waitcnt lgkmcnt(15)
	v_pk_fma_f32 v[76:77], v[196:197], v[172:173], v[222:223] op_sel_hi:[1,0,1]
	v_pk_fma_f32 v[84:85], v[196:197], v[174:175], v[230:231] op_sel_hi:[1,0,1]
	v_pk_fma_f32 v[78:79], v[198:199], v[172:173], v[224:225] op_sel_hi:[1,0,1]
	v_pk_fma_f32 v[86:87], v[198:199], v[174:175], v[234:235] op_sel_hi:[1,0,1]
	ds_read_b128 v[192:195], v2 offset:9216
	ds_read_b128 v[196:199], v2 offset:9232
	ds_write_b64 v1, v[160:161] offset:54272
	s_waitcnt lgkmcnt(15)
	v_pk_mul_f32 v[164:165], v[72:73], v[4:5]
	v_pk_mul_f32 v[166:167], v[80:81], v[4:5]
	s_waitcnt lgkmcnt(15)
	v_pk_mul_f32 v[168:169], v[72:73], v[208:209]
	v_pk_mul_f32 v[170:171], v[80:81], v[208:209]
	v_pk_fma_f32 v[164:165], v[74:75], v[6:7], v[164:165]
	v_pk_fma_f32 v[166:167], v[82:83], v[6:7], v[166:167]
	v_pk_fma_f32 v[168:169], v[74:75], v[210:211], v[168:169]
	v_pk_fma_f32 v[170:171], v[82:83], v[210:211], v[170:171]
	v_pk_fma_f32 v[164:165], v[76:77], v[8:9], v[164:165]
	v_pk_fma_f32 v[166:167], v[84:85], v[8:9], v[166:167]
	s_waitcnt lgkmcnt(15)
	v_pk_fma_f32 v[168:169], v[76:77], v[212:213], v[168:169]
	v_pk_fma_f32 v[170:171], v[84:85], v[212:213], v[170:171]
	v_pk_fma_f32 v[164:165], v[78:79], v[10:11], v[164:165]
	v_pk_fma_f32 v[166:167], v[86:87], v[10:11], v[166:167]
	v_pk_fma_f32 v[168:169], v[78:79], v[214:215], v[168:169]
	v_pk_fma_f32 v[170:171], v[86:87], v[214:215], v[170:171]
	s_waitcnt lgkmcnt(15)
	v_pk_mul_f32 v[218:219], v[26:27], v[40:41] op_sel_hi:[0,1]
	v_pk_mul_f32 v[226:227], v[26:27], v[40:41] op_sel:[1,0]
	ds_read_b128 v[4:7], v2 offset:5376
	v_pk_mul_f32 v[220:221], v[26:27], v[42:43] op_sel_hi:[0,1]
	v_pk_mul_f32 v[228:229], v[26:27], v[42:43] op_sel:[1,0]
	ds_read_b128 v[8:11], v2 offset:5392
	v_pk_mul_f32 v[222:223], v[26:27], v[44:45] op_sel_hi:[0,1]
	v_pk_mul_f32 v[230:231], v[26:27], v[44:45] op_sel:[1,0]
	ds_read_b128 v[208:211], v2 offset:17408
	v_pk_mul_f32 v[224:225], v[26:27], v[46:47] op_sel_hi:[0,1]
	v_pk_mul_f32 v[234:235], v[26:27], v[46:47] op_sel:[1,0]
	ds_read_b128 v[212:215], v2 offset:17424
	v_add_f32_e32 v172, v164, v165
	v_add_f32_e32 v174, v166, v167
	ds_read_b128 v[40:43], v2 offset:13568
	v_add_f32_e32 v160, v168, v169
	v_add_f32_e32 v161, v170, v171
	ds_read_b128 v[44:47], v2 offset:13584
	s_waitcnt lgkmcnt(15)
	v_pk_fma_f32 v[218:219], v[72:73], v[12:13], v[218:219]
	v_pk_fma_f32 v[226:227], v[80:81], v[12:13], v[226:227]
	ds_read_b64 v[26:27], v3 offset:42240
	v_pk_fma_f32 v[220:221], v[74:75], v[14:15], v[220:221]
	v_pk_fma_f32 v[228:229], v[82:83], v[14:15], v[228:229]
	v_add_f32_dpp v172, v172, v172 quad_perm:[1,0,3,2] row_mask:0xf bank_mask:0xf bound_ctrl:1
	v_add_f32_dpp v174, v174, v174 quad_perm:[1,0,3,2] row_mask:0xf bank_mask:0xf bound_ctrl:1
	v_add_f32_dpp v160, v160, v160 quad_perm:[1,0,3,2] row_mask:0xf bank_mask:0xf bound_ctrl:1
	v_add_f32_dpp v161, v161, v161 quad_perm:[1,0,3,2] row_mask:0xf bank_mask:0xf bound_ctrl:1
	s_waitcnt lgkmcnt(15)
	v_pk_fma_f32 v[222:223], v[76:77], v[28:29], v[222:223]
	v_pk_fma_f32 v[230:231], v[84:85], v[28:29], v[230:231]
	v_pk_fma_f32 v[224:225], v[78:79], v[30:31], v[224:225]
	v_pk_fma_f32 v[234:235], v[86:87], v[30:31], v[234:235]
	v_add_f32_dpp v172, v172, v172 quad_perm:[2,3,0,1] row_mask:0xf bank_mask:0xf bound_ctrl:1
	v_add_f32_dpp v174, v174, v174 quad_perm:[2,3,0,1] row_mask:0xf bank_mask:0xf bound_ctrl:1
	ds_read_b128 v[12:15], v2 offset:1280
	v_add_f32_dpp v160, v160, v160 quad_perm:[2,3,0,1] row_mask:0xf bank_mask:0xf bound_ctrl:1
	v_add_f32_dpp v161, v161, v161 quad_perm:[2,3,0,1] row_mask:0xf bank_mask:0xf bound_ctrl:1
	ds_read_b128 v[28:31], v2 offset:1296
	v_add_f32_dpp v172, v172, v172 row_half_mirror row_mask:0xf bank_mask:0xf bound_ctrl:1
	v_add_f32_dpp v174, v174, v174 row_half_mirror row_mask:0xf bank_mask:0xf bound_ctrl:1
	v_add_f32_dpp v160, v160, v160 row_half_mirror row_mask:0xf bank_mask:0xf bound_ctrl:1
	v_add_f32_dpp v161, v161, v161 row_half_mirror row_mask:0xf bank_mask:0xf bound_ctrl:1
	s_waitcnt lgkmcnt(15)
	v_pk_fma_f32 v[72:73], v[32:33], v[172:173], v[218:219] op_sel_hi:[1,0,1]
	v_pk_fma_f32 v[80:81], v[32:33], v[174:175], v[226:227] op_sel_hi:[1,0,1]
	v_pk_fma_f32 v[74:75], v[34:35], v[172:173], v[220:221] op_sel_hi:[1,0,1]
	v_pk_fma_f32 v[82:83], v[34:35], v[174:175], v[228:229] op_sel_hi:[1,0,1]
	s_waitcnt lgkmcnt(15)
	v_pk_fma_f32 v[76:77], v[36:37], v[172:173], v[222:223] op_sel_hi:[1,0,1]
	v_pk_fma_f32 v[84:85], v[36:37], v[174:175], v[230:231] op_sel_hi:[1,0,1]
	v_pk_fma_f32 v[78:79], v[38:39], v[172:173], v[224:225] op_sel_hi:[1,0,1]
	v_pk_fma_f32 v[86:87], v[38:39], v[174:175], v[234:235] op_sel_hi:[1,0,1]
	ds_read_b128 v[32:35], v2 offset:9472
	ds_read_b128 v[36:39], v2 offset:9488
	ds_write_b64 v1, v[160:161] offset:54528
	s_waitcnt lgkmcnt(15)
	v_pk_mul_f32 v[164:165], v[72:73], v[176:177]
	v_pk_mul_f32 v[166:167], v[80:81], v[176:177]
	s_waitcnt lgkmcnt(15)
	v_pk_mul_f32 v[168:169], v[72:73], v[48:49]
	v_pk_mul_f32 v[170:171], v[80:81], v[48:49]
	v_pk_fma_f32 v[164:165], v[74:75], v[178:179], v[164:165]
	v_pk_fma_f32 v[166:167], v[82:83], v[178:179], v[166:167]
	v_pk_fma_f32 v[168:169], v[74:75], v[50:51], v[168:169]
	v_pk_fma_f32 v[170:171], v[82:83], v[50:51], v[170:171]
	v_pk_fma_f32 v[164:165], v[76:77], v[180:181], v[164:165]
	v_pk_fma_f32 v[166:167], v[84:85], v[180:181], v[166:167]
	s_waitcnt lgkmcnt(15)
	v_pk_fma_f32 v[168:169], v[76:77], v[52:53], v[168:169]
	v_pk_fma_f32 v[170:171], v[84:85], v[52:53], v[170:171]
	v_pk_fma_f32 v[164:165], v[78:79], v[182:183], v[164:165]
	v_pk_fma_f32 v[166:167], v[86:87], v[182:183], v[166:167]
	v_pk_fma_f32 v[168:169], v[78:79], v[54:55], v[168:169]
	v_pk_fma_f32 v[170:171], v[86:87], v[54:55], v[170:171]
	s_waitcnt lgkmcnt(15)
	v_pk_mul_f32 v[218:219], v[216:217], v[200:201] op_sel_hi:[0,1]
	v_pk_mul_f32 v[226:227], v[216:217], v[200:201] op_sel:[1,0]
	ds_read_b128 v[176:179], v2 offset:5632
	v_pk_mul_f32 v[220:221], v[216:217], v[202:203] op_sel_hi:[0,1]
	v_pk_mul_f32 v[228:229], v[216:217], v[202:203] op_sel:[1,0]
	ds_read_b128 v[180:183], v2 offset:5648
	v_pk_mul_f32 v[222:223], v[216:217], v[204:205] op_sel_hi:[0,1]
	v_pk_mul_f32 v[230:231], v[216:217], v[204:205] op_sel:[1,0]
	ds_read_b128 v[48:51], v2 offset:17664
	v_pk_mul_f32 v[224:225], v[216:217], v[206:207] op_sel_hi:[0,1]
	v_pk_mul_f32 v[234:235], v[216:217], v[206:207] op_sel:[1,0]
	ds_read_b128 v[52:55], v2 offset:17680
	v_add_f32_e32 v172, v164, v165
	v_add_f32_e32 v174, v166, v167
	ds_read_b128 v[200:203], v2 offset:13824
	v_add_f32_e32 v160, v168, v169
	v_add_f32_e32 v161, v170, v171
	ds_read_b128 v[204:207], v2 offset:13840
	s_waitcnt lgkmcnt(15)
	v_pk_fma_f32 v[218:219], v[72:73], v[184:185], v[218:219]
	v_pk_fma_f32 v[226:227], v[80:81], v[184:185], v[226:227]
	ds_read_b64 v[216:217], v3 offset:42496
	v_pk_fma_f32 v[220:221], v[74:75], v[186:187], v[220:221]
	v_pk_fma_f32 v[228:229], v[82:83], v[186:187], v[228:229]
	v_add_f32_dpp v172, v172, v172 quad_perm:[1,0,3,2] row_mask:0xf bank_mask:0xf bound_ctrl:1
	v_add_f32_dpp v174, v174, v174 quad_perm:[1,0,3,2] row_mask:0xf bank_mask:0xf bound_ctrl:1
	v_add_f32_dpp v160, v160, v160 quad_perm:[1,0,3,2] row_mask:0xf bank_mask:0xf bound_ctrl:1
	v_add_f32_dpp v161, v161, v161 quad_perm:[1,0,3,2] row_mask:0xf bank_mask:0xf bound_ctrl:1
	s_waitcnt lgkmcnt(15)
	v_pk_fma_f32 v[222:223], v[76:77], v[188:189], v[222:223]
	v_pk_fma_f32 v[230:231], v[84:85], v[188:189], v[230:231]
	v_pk_fma_f32 v[224:225], v[78:79], v[190:191], v[224:225]
	v_pk_fma_f32 v[234:235], v[86:87], v[190:191], v[234:235]
	v_add_f32_dpp v172, v172, v172 quad_perm:[2,3,0,1] row_mask:0xf bank_mask:0xf bound_ctrl:1
	v_add_f32_dpp v174, v174, v174 quad_perm:[2,3,0,1] row_mask:0xf bank_mask:0xf bound_ctrl:1
	ds_read_b128 v[184:187], v2 offset:1536
	v_add_f32_dpp v160, v160, v160 quad_perm:[2,3,0,1] row_mask:0xf bank_mask:0xf bound_ctrl:1
	v_add_f32_dpp v161, v161, v161 quad_perm:[2,3,0,1] row_mask:0xf bank_mask:0xf bound_ctrl:1
	ds_read_b128 v[188:191], v2 offset:1552
	v_add_f32_dpp v172, v172, v172 row_half_mirror row_mask:0xf bank_mask:0xf bound_ctrl:1
	v_add_f32_dpp v174, v174, v174 row_half_mirror row_mask:0xf bank_mask:0xf bound_ctrl:1
	v_add_f32_dpp v160, v160, v160 row_half_mirror row_mask:0xf bank_mask:0xf bound_ctrl:1
	v_add_f32_dpp v161, v161, v161 row_half_mirror row_mask:0xf bank_mask:0xf bound_ctrl:1
	s_waitcnt lgkmcnt(15)
	v_pk_fma_f32 v[72:73], v[192:193], v[172:173], v[218:219] op_sel_hi:[1,0,1]
	v_pk_fma_f32 v[80:81], v[192:193], v[174:175], v[226:227] op_sel_hi:[1,0,1]
	v_pk_fma_f32 v[74:75], v[194:195], v[172:173], v[220:221] op_sel_hi:[1,0,1]
	v_pk_fma_f32 v[82:83], v[194:195], v[174:175], v[228:229] op_sel_hi:[1,0,1]
	s_waitcnt lgkmcnt(15)
	v_pk_fma_f32 v[76:77], v[196:197], v[172:173], v[222:223] op_sel_hi:[1,0,1]
	v_pk_fma_f32 v[84:85], v[196:197], v[174:175], v[230:231] op_sel_hi:[1,0,1]
	v_pk_fma_f32 v[78:79], v[198:199], v[172:173], v[224:225] op_sel_hi:[1,0,1]
	v_pk_fma_f32 v[86:87], v[198:199], v[174:175], v[234:235] op_sel_hi:[1,0,1]
	ds_read_b128 v[192:195], v2 offset:9728
	ds_read_b128 v[196:199], v2 offset:9744
	ds_write_b64 v1, v[160:161] offset:54784
	s_waitcnt lgkmcnt(15)
	v_pk_mul_f32 v[164:165], v[72:73], v[4:5]
	v_pk_mul_f32 v[166:167], v[80:81], v[4:5]
	s_waitcnt lgkmcnt(15)
	v_pk_mul_f32 v[168:169], v[72:73], v[208:209]
	v_pk_mul_f32 v[170:171], v[80:81], v[208:209]
	v_pk_fma_f32 v[164:165], v[74:75], v[6:7], v[164:165]
	v_pk_fma_f32 v[166:167], v[82:83], v[6:7], v[166:167]
	v_pk_fma_f32 v[168:169], v[74:75], v[210:211], v[168:169]
	v_pk_fma_f32 v[170:171], v[82:83], v[210:211], v[170:171]
	v_pk_fma_f32 v[164:165], v[76:77], v[8:9], v[164:165]
	v_pk_fma_f32 v[166:167], v[84:85], v[8:9], v[166:167]
	s_waitcnt lgkmcnt(15)
	v_pk_fma_f32 v[168:169], v[76:77], v[212:213], v[168:169]
	v_pk_fma_f32 v[170:171], v[84:85], v[212:213], v[170:171]
	v_pk_fma_f32 v[164:165], v[78:79], v[10:11], v[164:165]
	v_pk_fma_f32 v[166:167], v[86:87], v[10:11], v[166:167]
	v_pk_fma_f32 v[168:169], v[78:79], v[214:215], v[168:169]
	v_pk_fma_f32 v[170:171], v[86:87], v[214:215], v[170:171]
	s_waitcnt lgkmcnt(15)
	v_pk_mul_f32 v[218:219], v[26:27], v[40:41] op_sel_hi:[0,1]
	v_pk_mul_f32 v[226:227], v[26:27], v[40:41] op_sel:[1,0]
	ds_read_b128 v[4:7], v2 offset:5888
	v_pk_mul_f32 v[220:221], v[26:27], v[42:43] op_sel_hi:[0,1]
	v_pk_mul_f32 v[228:229], v[26:27], v[42:43] op_sel:[1,0]
	ds_read_b128 v[8:11], v2 offset:5904
	v_pk_mul_f32 v[222:223], v[26:27], v[44:45] op_sel_hi:[0,1]
	v_pk_mul_f32 v[230:231], v[26:27], v[44:45] op_sel:[1,0]
	ds_read_b128 v[208:211], v2 offset:17920
	v_pk_mul_f32 v[224:225], v[26:27], v[46:47] op_sel_hi:[0,1]
	v_pk_mul_f32 v[234:235], v[26:27], v[46:47] op_sel:[1,0]
	ds_read_b128 v[212:215], v2 offset:17936
	v_add_f32_e32 v172, v164, v165
	v_add_f32_e32 v174, v166, v167
	ds_read_b128 v[40:43], v2 offset:14080
	v_add_f32_e32 v160, v168, v169
	v_add_f32_e32 v161, v170, v171
	ds_read_b128 v[44:47], v2 offset:14096
	s_waitcnt lgkmcnt(15)
	v_pk_fma_f32 v[218:219], v[72:73], v[12:13], v[218:219]
	v_pk_fma_f32 v[226:227], v[80:81], v[12:13], v[226:227]
	ds_read_b64 v[26:27], v3 offset:42752
	v_pk_fma_f32 v[220:221], v[74:75], v[14:15], v[220:221]
	v_pk_fma_f32 v[228:229], v[82:83], v[14:15], v[228:229]
	v_add_f32_dpp v172, v172, v172 quad_perm:[1,0,3,2] row_mask:0xf bank_mask:0xf bound_ctrl:1
	v_add_f32_dpp v174, v174, v174 quad_perm:[1,0,3,2] row_mask:0xf bank_mask:0xf bound_ctrl:1
	v_add_f32_dpp v160, v160, v160 quad_perm:[1,0,3,2] row_mask:0xf bank_mask:0xf bound_ctrl:1
	v_add_f32_dpp v161, v161, v161 quad_perm:[1,0,3,2] row_mask:0xf bank_mask:0xf bound_ctrl:1
	s_waitcnt lgkmcnt(15)
	v_pk_fma_f32 v[222:223], v[76:77], v[28:29], v[222:223]
	v_pk_fma_f32 v[230:231], v[84:85], v[28:29], v[230:231]
	v_pk_fma_f32 v[224:225], v[78:79], v[30:31], v[224:225]
	v_pk_fma_f32 v[234:235], v[86:87], v[30:31], v[234:235]
	v_add_f32_dpp v172, v172, v172 quad_perm:[2,3,0,1] row_mask:0xf bank_mask:0xf bound_ctrl:1
	v_add_f32_dpp v174, v174, v174 quad_perm:[2,3,0,1] row_mask:0xf bank_mask:0xf bound_ctrl:1
	ds_read_b128 v[12:15], v2 offset:1792
	v_add_f32_dpp v160, v160, v160 quad_perm:[2,3,0,1] row_mask:0xf bank_mask:0xf bound_ctrl:1
	v_add_f32_dpp v161, v161, v161 quad_perm:[2,3,0,1] row_mask:0xf bank_mask:0xf bound_ctrl:1
	ds_read_b128 v[28:31], v2 offset:1808
	v_add_f32_dpp v172, v172, v172 row_half_mirror row_mask:0xf bank_mask:0xf bound_ctrl:1
	v_add_f32_dpp v174, v174, v174 row_half_mirror row_mask:0xf bank_mask:0xf bound_ctrl:1
	v_add_f32_dpp v160, v160, v160 row_half_mirror row_mask:0xf bank_mask:0xf bound_ctrl:1
	v_add_f32_dpp v161, v161, v161 row_half_mirror row_mask:0xf bank_mask:0xf bound_ctrl:1
	s_waitcnt lgkmcnt(15)
	v_pk_fma_f32 v[72:73], v[32:33], v[172:173], v[218:219] op_sel_hi:[1,0,1]
	v_pk_fma_f32 v[80:81], v[32:33], v[174:175], v[226:227] op_sel_hi:[1,0,1]
	v_pk_fma_f32 v[74:75], v[34:35], v[172:173], v[220:221] op_sel_hi:[1,0,1]
	v_pk_fma_f32 v[82:83], v[34:35], v[174:175], v[228:229] op_sel_hi:[1,0,1]
	s_waitcnt lgkmcnt(15)
	v_pk_fma_f32 v[76:77], v[36:37], v[172:173], v[222:223] op_sel_hi:[1,0,1]
	v_pk_fma_f32 v[84:85], v[36:37], v[174:175], v[230:231] op_sel_hi:[1,0,1]
	v_pk_fma_f32 v[78:79], v[38:39], v[172:173], v[224:225] op_sel_hi:[1,0,1]
	v_pk_fma_f32 v[86:87], v[38:39], v[174:175], v[234:235] op_sel_hi:[1,0,1]
	ds_read_b128 v[32:35], v2 offset:9984
	ds_read_b128 v[36:39], v2 offset:10000
	ds_write_b64 v1, v[160:161] offset:55040
	s_waitcnt lgkmcnt(15)
	v_pk_mul_f32 v[164:165], v[72:73], v[176:177]
	v_pk_mul_f32 v[166:167], v[80:81], v[176:177]
	s_waitcnt lgkmcnt(15)
	v_pk_mul_f32 v[168:169], v[72:73], v[48:49]
	v_pk_mul_f32 v[170:171], v[80:81], v[48:49]
	v_pk_fma_f32 v[164:165], v[74:75], v[178:179], v[164:165]
	v_pk_fma_f32 v[166:167], v[82:83], v[178:179], v[166:167]
	v_pk_fma_f32 v[168:169], v[74:75], v[50:51], v[168:169]
	v_pk_fma_f32 v[170:171], v[82:83], v[50:51], v[170:171]
	v_pk_fma_f32 v[164:165], v[76:77], v[180:181], v[164:165]
	v_pk_fma_f32 v[166:167], v[84:85], v[180:181], v[166:167]
	s_waitcnt lgkmcnt(15)
	v_pk_fma_f32 v[168:169], v[76:77], v[52:53], v[168:169]
	v_pk_fma_f32 v[170:171], v[84:85], v[52:53], v[170:171]
	v_pk_fma_f32 v[164:165], v[78:79], v[182:183], v[164:165]
	v_pk_fma_f32 v[166:167], v[86:87], v[182:183], v[166:167]
	v_pk_fma_f32 v[168:169], v[78:79], v[54:55], v[168:169]
	v_pk_fma_f32 v[170:171], v[86:87], v[54:55], v[170:171]
	s_waitcnt lgkmcnt(15)
	v_pk_mul_f32 v[218:219], v[216:217], v[200:201] op_sel_hi:[0,1]
	v_pk_mul_f32 v[226:227], v[216:217], v[200:201] op_sel:[1,0]
	ds_read_b128 v[176:179], v2 offset:6144
	v_pk_mul_f32 v[220:221], v[216:217], v[202:203] op_sel_hi:[0,1]
	v_pk_mul_f32 v[228:229], v[216:217], v[202:203] op_sel:[1,0]
	ds_read_b128 v[180:183], v2 offset:6160
	v_pk_mul_f32 v[222:223], v[216:217], v[204:205] op_sel_hi:[0,1]
	v_pk_mul_f32 v[230:231], v[216:217], v[204:205] op_sel:[1,0]
	ds_read_b128 v[48:51], v2 offset:18176
	v_pk_mul_f32 v[224:225], v[216:217], v[206:207] op_sel_hi:[0,1]
	v_pk_mul_f32 v[234:235], v[216:217], v[206:207] op_sel:[1,0]
	ds_read_b128 v[52:55], v2 offset:18192
	v_add_f32_e32 v172, v164, v165
	v_add_f32_e32 v174, v166, v167
	ds_read_b128 v[200:203], v2 offset:14336
	v_add_f32_e32 v160, v168, v169
	v_add_f32_e32 v161, v170, v171
	ds_read_b128 v[204:207], v2 offset:14352
	s_waitcnt lgkmcnt(15)
	v_pk_fma_f32 v[218:219], v[72:73], v[184:185], v[218:219]
	v_pk_fma_f32 v[226:227], v[80:81], v[184:185], v[226:227]
	ds_read_b64 v[216:217], v3 offset:43008
	v_pk_fma_f32 v[220:221], v[74:75], v[186:187], v[220:221]
	v_pk_fma_f32 v[228:229], v[82:83], v[186:187], v[228:229]
	v_add_f32_dpp v172, v172, v172 quad_perm:[1,0,3,2] row_mask:0xf bank_mask:0xf bound_ctrl:1
	v_add_f32_dpp v174, v174, v174 quad_perm:[1,0,3,2] row_mask:0xf bank_mask:0xf bound_ctrl:1
	v_add_f32_dpp v160, v160, v160 quad_perm:[1,0,3,2] row_mask:0xf bank_mask:0xf bound_ctrl:1
	v_add_f32_dpp v161, v161, v161 quad_perm:[1,0,3,2] row_mask:0xf bank_mask:0xf bound_ctrl:1
	s_waitcnt lgkmcnt(15)
	v_pk_fma_f32 v[222:223], v[76:77], v[188:189], v[222:223]
	v_pk_fma_f32 v[230:231], v[84:85], v[188:189], v[230:231]
	v_pk_fma_f32 v[224:225], v[78:79], v[190:191], v[224:225]
	v_pk_fma_f32 v[234:235], v[86:87], v[190:191], v[234:235]
	v_add_f32_dpp v172, v172, v172 quad_perm:[2,3,0,1] row_mask:0xf bank_mask:0xf bound_ctrl:1
	v_add_f32_dpp v174, v174, v174 quad_perm:[2,3,0,1] row_mask:0xf bank_mask:0xf bound_ctrl:1
	ds_read_b128 v[184:187], v2 offset:2048
	v_add_f32_dpp v160, v160, v160 quad_perm:[2,3,0,1] row_mask:0xf bank_mask:0xf bound_ctrl:1
	v_add_f32_dpp v161, v161, v161 quad_perm:[2,3,0,1] row_mask:0xf bank_mask:0xf bound_ctrl:1
	ds_read_b128 v[188:191], v2 offset:2064
	v_add_f32_dpp v172, v172, v172 row_half_mirror row_mask:0xf bank_mask:0xf bound_ctrl:1
	v_add_f32_dpp v174, v174, v174 row_half_mirror row_mask:0xf bank_mask:0xf bound_ctrl:1
	v_add_f32_dpp v160, v160, v160 row_half_mirror row_mask:0xf bank_mask:0xf bound_ctrl:1
	v_add_f32_dpp v161, v161, v161 row_half_mirror row_mask:0xf bank_mask:0xf bound_ctrl:1
	s_waitcnt lgkmcnt(15)
	v_pk_fma_f32 v[72:73], v[192:193], v[172:173], v[218:219] op_sel_hi:[1,0,1]
	v_pk_fma_f32 v[80:81], v[192:193], v[174:175], v[226:227] op_sel_hi:[1,0,1]
	v_pk_fma_f32 v[74:75], v[194:195], v[172:173], v[220:221] op_sel_hi:[1,0,1]
	v_pk_fma_f32 v[82:83], v[194:195], v[174:175], v[228:229] op_sel_hi:[1,0,1]
	s_waitcnt lgkmcnt(15)
	v_pk_fma_f32 v[76:77], v[196:197], v[172:173], v[222:223] op_sel_hi:[1,0,1]
	v_pk_fma_f32 v[84:85], v[196:197], v[174:175], v[230:231] op_sel_hi:[1,0,1]
	v_pk_fma_f32 v[78:79], v[198:199], v[172:173], v[224:225] op_sel_hi:[1,0,1]
	v_pk_fma_f32 v[86:87], v[198:199], v[174:175], v[234:235] op_sel_hi:[1,0,1]
	ds_read_b128 v[192:195], v2 offset:10240
	ds_read_b128 v[196:199], v2 offset:10256
	ds_write_b64 v1, v[160:161] offset:55296
	s_waitcnt lgkmcnt(15)
	v_pk_mul_f32 v[164:165], v[72:73], v[4:5]
	v_pk_mul_f32 v[166:167], v[80:81], v[4:5]
	s_waitcnt lgkmcnt(15)
	v_pk_mul_f32 v[168:169], v[72:73], v[208:209]
	v_pk_mul_f32 v[170:171], v[80:81], v[208:209]
	v_pk_fma_f32 v[164:165], v[74:75], v[6:7], v[164:165]
	v_pk_fma_f32 v[166:167], v[82:83], v[6:7], v[166:167]
	v_pk_fma_f32 v[168:169], v[74:75], v[210:211], v[168:169]
	v_pk_fma_f32 v[170:171], v[82:83], v[210:211], v[170:171]
	v_pk_fma_f32 v[164:165], v[76:77], v[8:9], v[164:165]
	v_pk_fma_f32 v[166:167], v[84:85], v[8:9], v[166:167]
	s_waitcnt lgkmcnt(15)
	v_pk_fma_f32 v[168:169], v[76:77], v[212:213], v[168:169]
	v_pk_fma_f32 v[170:171], v[84:85], v[212:213], v[170:171]
	v_pk_fma_f32 v[164:165], v[78:79], v[10:11], v[164:165]
	v_pk_fma_f32 v[166:167], v[86:87], v[10:11], v[166:167]
	v_pk_fma_f32 v[168:169], v[78:79], v[214:215], v[168:169]
	v_pk_fma_f32 v[170:171], v[86:87], v[214:215], v[170:171]
	s_waitcnt lgkmcnt(15)
	v_pk_mul_f32 v[218:219], v[26:27], v[40:41] op_sel_hi:[0,1]
	v_pk_mul_f32 v[226:227], v[26:27], v[40:41] op_sel:[1,0]
	ds_read_b128 v[4:7], v2 offset:6400
	v_pk_mul_f32 v[220:221], v[26:27], v[42:43] op_sel_hi:[0,1]
	v_pk_mul_f32 v[228:229], v[26:27], v[42:43] op_sel:[1,0]
	ds_read_b128 v[8:11], v2 offset:6416
	v_pk_mul_f32 v[222:223], v[26:27], v[44:45] op_sel_hi:[0,1]
	v_pk_mul_f32 v[230:231], v[26:27], v[44:45] op_sel:[1,0]
	ds_read_b128 v[208:211], v2 offset:18432
	v_pk_mul_f32 v[224:225], v[26:27], v[46:47] op_sel_hi:[0,1]
	v_pk_mul_f32 v[234:235], v[26:27], v[46:47] op_sel:[1,0]
	ds_read_b128 v[212:215], v2 offset:18448
	v_add_f32_e32 v172, v164, v165
	v_add_f32_e32 v174, v166, v167
	ds_read_b128 v[40:43], v2 offset:14592
	v_add_f32_e32 v160, v168, v169
	v_add_f32_e32 v161, v170, v171
	ds_read_b128 v[44:47], v2 offset:14608
	s_waitcnt lgkmcnt(15)
	v_pk_fma_f32 v[218:219], v[72:73], v[12:13], v[218:219]
	v_pk_fma_f32 v[226:227], v[80:81], v[12:13], v[226:227]
	ds_read_b64 v[26:27], v3 offset:43264
	v_pk_fma_f32 v[220:221], v[74:75], v[14:15], v[220:221]
	v_pk_fma_f32 v[228:229], v[82:83], v[14:15], v[228:229]
	v_add_f32_dpp v172, v172, v172 quad_perm:[1,0,3,2] row_mask:0xf bank_mask:0xf bound_ctrl:1
	v_add_f32_dpp v174, v174, v174 quad_perm:[1,0,3,2] row_mask:0xf bank_mask:0xf bound_ctrl:1
	v_add_f32_dpp v160, v160, v160 quad_perm:[1,0,3,2] row_mask:0xf bank_mask:0xf bound_ctrl:1
	v_add_f32_dpp v161, v161, v161 quad_perm:[1,0,3,2] row_mask:0xf bank_mask:0xf bound_ctrl:1
	s_waitcnt lgkmcnt(15)
	v_pk_fma_f32 v[222:223], v[76:77], v[28:29], v[222:223]
	v_pk_fma_f32 v[230:231], v[84:85], v[28:29], v[230:231]
	v_pk_fma_f32 v[224:225], v[78:79], v[30:31], v[224:225]
	v_pk_fma_f32 v[234:235], v[86:87], v[30:31], v[234:235]
	v_add_f32_dpp v172, v172, v172 quad_perm:[2,3,0,1] row_mask:0xf bank_mask:0xf bound_ctrl:1
	v_add_f32_dpp v174, v174, v174 quad_perm:[2,3,0,1] row_mask:0xf bank_mask:0xf bound_ctrl:1
	ds_read_b128 v[12:15], v2 offset:2304
	v_add_f32_dpp v160, v160, v160 quad_perm:[2,3,0,1] row_mask:0xf bank_mask:0xf bound_ctrl:1
	v_add_f32_dpp v161, v161, v161 quad_perm:[2,3,0,1] row_mask:0xf bank_mask:0xf bound_ctrl:1
	ds_read_b128 v[28:31], v2 offset:2320
	v_add_f32_dpp v172, v172, v172 row_half_mirror row_mask:0xf bank_mask:0xf bound_ctrl:1
	v_add_f32_dpp v174, v174, v174 row_half_mirror row_mask:0xf bank_mask:0xf bound_ctrl:1
	v_add_f32_dpp v160, v160, v160 row_half_mirror row_mask:0xf bank_mask:0xf bound_ctrl:1
	v_add_f32_dpp v161, v161, v161 row_half_mirror row_mask:0xf bank_mask:0xf bound_ctrl:1
	s_waitcnt lgkmcnt(15)
	v_pk_fma_f32 v[72:73], v[32:33], v[172:173], v[218:219] op_sel_hi:[1,0,1]
	v_pk_fma_f32 v[80:81], v[32:33], v[174:175], v[226:227] op_sel_hi:[1,0,1]
	v_pk_fma_f32 v[74:75], v[34:35], v[172:173], v[220:221] op_sel_hi:[1,0,1]
	v_pk_fma_f32 v[82:83], v[34:35], v[174:175], v[228:229] op_sel_hi:[1,0,1]
	s_waitcnt lgkmcnt(15)
	v_pk_fma_f32 v[76:77], v[36:37], v[172:173], v[222:223] op_sel_hi:[1,0,1]
	v_pk_fma_f32 v[84:85], v[36:37], v[174:175], v[230:231] op_sel_hi:[1,0,1]
	v_pk_fma_f32 v[78:79], v[38:39], v[172:173], v[224:225] op_sel_hi:[1,0,1]
	v_pk_fma_f32 v[86:87], v[38:39], v[174:175], v[234:235] op_sel_hi:[1,0,1]
	ds_read_b128 v[32:35], v2 offset:10496
	ds_read_b128 v[36:39], v2 offset:10512
	ds_write_b64 v1, v[160:161] offset:55552
	s_waitcnt lgkmcnt(15)
	v_pk_mul_f32 v[164:165], v[72:73], v[176:177]
	v_pk_mul_f32 v[166:167], v[80:81], v[176:177]
	s_waitcnt lgkmcnt(15)
	v_pk_mul_f32 v[168:169], v[72:73], v[48:49]
	v_pk_mul_f32 v[170:171], v[80:81], v[48:49]
	v_pk_fma_f32 v[164:165], v[74:75], v[178:179], v[164:165]
	v_pk_fma_f32 v[166:167], v[82:83], v[178:179], v[166:167]
	v_pk_fma_f32 v[168:169], v[74:75], v[50:51], v[168:169]
	v_pk_fma_f32 v[170:171], v[82:83], v[50:51], v[170:171]
	v_pk_fma_f32 v[164:165], v[76:77], v[180:181], v[164:165]
	v_pk_fma_f32 v[166:167], v[84:85], v[180:181], v[166:167]
	s_waitcnt lgkmcnt(15)
	v_pk_fma_f32 v[168:169], v[76:77], v[52:53], v[168:169]
	v_pk_fma_f32 v[170:171], v[84:85], v[52:53], v[170:171]
	v_pk_fma_f32 v[164:165], v[78:79], v[182:183], v[164:165]
	v_pk_fma_f32 v[166:167], v[86:87], v[182:183], v[166:167]
	v_pk_fma_f32 v[168:169], v[78:79], v[54:55], v[168:169]
	v_pk_fma_f32 v[170:171], v[86:87], v[54:55], v[170:171]
	s_waitcnt lgkmcnt(15)
	v_pk_mul_f32 v[218:219], v[216:217], v[200:201] op_sel_hi:[0,1]
	v_pk_mul_f32 v[226:227], v[216:217], v[200:201] op_sel:[1,0]
	ds_read_b128 v[176:179], v2 offset:6656
	v_pk_mul_f32 v[220:221], v[216:217], v[202:203] op_sel_hi:[0,1]
	v_pk_mul_f32 v[228:229], v[216:217], v[202:203] op_sel:[1,0]
	ds_read_b128 v[180:183], v2 offset:6672
	v_pk_mul_f32 v[222:223], v[216:217], v[204:205] op_sel_hi:[0,1]
	v_pk_mul_f32 v[230:231], v[216:217], v[204:205] op_sel:[1,0]
	ds_read_b128 v[48:51], v2 offset:18688
	v_pk_mul_f32 v[224:225], v[216:217], v[206:207] op_sel_hi:[0,1]
	v_pk_mul_f32 v[234:235], v[216:217], v[206:207] op_sel:[1,0]
	ds_read_b128 v[52:55], v2 offset:18704
	v_add_f32_e32 v172, v164, v165
	v_add_f32_e32 v174, v166, v167
	ds_read_b128 v[200:203], v2 offset:14848
	v_add_f32_e32 v160, v168, v169
	v_add_f32_e32 v161, v170, v171
	ds_read_b128 v[204:207], v2 offset:14864
	s_waitcnt lgkmcnt(15)
	v_pk_fma_f32 v[218:219], v[72:73], v[184:185], v[218:219]
	v_pk_fma_f32 v[226:227], v[80:81], v[184:185], v[226:227]
	ds_read_b64 v[216:217], v3 offset:43520
	v_pk_fma_f32 v[220:221], v[74:75], v[186:187], v[220:221]
	v_pk_fma_f32 v[228:229], v[82:83], v[186:187], v[228:229]
	v_add_f32_dpp v172, v172, v172 quad_perm:[1,0,3,2] row_mask:0xf bank_mask:0xf bound_ctrl:1
	v_add_f32_dpp v174, v174, v174 quad_perm:[1,0,3,2] row_mask:0xf bank_mask:0xf bound_ctrl:1
	v_add_f32_dpp v160, v160, v160 quad_perm:[1,0,3,2] row_mask:0xf bank_mask:0xf bound_ctrl:1
	v_add_f32_dpp v161, v161, v161 quad_perm:[1,0,3,2] row_mask:0xf bank_mask:0xf bound_ctrl:1
	s_waitcnt lgkmcnt(15)
	v_pk_fma_f32 v[222:223], v[76:77], v[188:189], v[222:223]
	v_pk_fma_f32 v[230:231], v[84:85], v[188:189], v[230:231]
	v_pk_fma_f32 v[224:225], v[78:79], v[190:191], v[224:225]
	v_pk_fma_f32 v[234:235], v[86:87], v[190:191], v[234:235]
	v_add_f32_dpp v172, v172, v172 quad_perm:[2,3,0,1] row_mask:0xf bank_mask:0xf bound_ctrl:1
	v_add_f32_dpp v174, v174, v174 quad_perm:[2,3,0,1] row_mask:0xf bank_mask:0xf bound_ctrl:1
	ds_read_b128 v[184:187], v2 offset:2560
	v_add_f32_dpp v160, v160, v160 quad_perm:[2,3,0,1] row_mask:0xf bank_mask:0xf bound_ctrl:1
	v_add_f32_dpp v161, v161, v161 quad_perm:[2,3,0,1] row_mask:0xf bank_mask:0xf bound_ctrl:1
	ds_read_b128 v[188:191], v2 offset:2576
	v_add_f32_dpp v172, v172, v172 row_half_mirror row_mask:0xf bank_mask:0xf bound_ctrl:1
	v_add_f32_dpp v174, v174, v174 row_half_mirror row_mask:0xf bank_mask:0xf bound_ctrl:1
	v_add_f32_dpp v160, v160, v160 row_half_mirror row_mask:0xf bank_mask:0xf bound_ctrl:1
	v_add_f32_dpp v161, v161, v161 row_half_mirror row_mask:0xf bank_mask:0xf bound_ctrl:1
	s_waitcnt lgkmcnt(15)
	v_pk_fma_f32 v[72:73], v[192:193], v[172:173], v[218:219] op_sel_hi:[1,0,1]
	v_pk_fma_f32 v[80:81], v[192:193], v[174:175], v[226:227] op_sel_hi:[1,0,1]
	v_pk_fma_f32 v[74:75], v[194:195], v[172:173], v[220:221] op_sel_hi:[1,0,1]
	v_pk_fma_f32 v[82:83], v[194:195], v[174:175], v[228:229] op_sel_hi:[1,0,1]
	s_waitcnt lgkmcnt(15)
	v_pk_fma_f32 v[76:77], v[196:197], v[172:173], v[222:223] op_sel_hi:[1,0,1]
	v_pk_fma_f32 v[84:85], v[196:197], v[174:175], v[230:231] op_sel_hi:[1,0,1]
	v_pk_fma_f32 v[78:79], v[198:199], v[172:173], v[224:225] op_sel_hi:[1,0,1]
	v_pk_fma_f32 v[86:87], v[198:199], v[174:175], v[234:235] op_sel_hi:[1,0,1]
	ds_read_b128 v[192:195], v2 offset:10752
	ds_read_b128 v[196:199], v2 offset:10768
	ds_write_b64 v1, v[160:161] offset:55808
	s_waitcnt lgkmcnt(15)
	v_pk_mul_f32 v[164:165], v[72:73], v[4:5]
	v_pk_mul_f32 v[166:167], v[80:81], v[4:5]
	s_waitcnt lgkmcnt(15)
	v_pk_mul_f32 v[168:169], v[72:73], v[208:209]
	v_pk_mul_f32 v[170:171], v[80:81], v[208:209]
	v_pk_fma_f32 v[164:165], v[74:75], v[6:7], v[164:165]
	v_pk_fma_f32 v[166:167], v[82:83], v[6:7], v[166:167]
	v_pk_fma_f32 v[168:169], v[74:75], v[210:211], v[168:169]
	v_pk_fma_f32 v[170:171], v[82:83], v[210:211], v[170:171]
	v_pk_fma_f32 v[164:165], v[76:77], v[8:9], v[164:165]
	v_pk_fma_f32 v[166:167], v[84:85], v[8:9], v[166:167]
	s_waitcnt lgkmcnt(15)
	v_pk_fma_f32 v[168:169], v[76:77], v[212:213], v[168:169]
	v_pk_fma_f32 v[170:171], v[84:85], v[212:213], v[170:171]
	v_pk_fma_f32 v[164:165], v[78:79], v[10:11], v[164:165]
	v_pk_fma_f32 v[166:167], v[86:87], v[10:11], v[166:167]
	v_pk_fma_f32 v[168:169], v[78:79], v[214:215], v[168:169]
	v_pk_fma_f32 v[170:171], v[86:87], v[214:215], v[170:171]
	s_waitcnt lgkmcnt(15)
	v_pk_mul_f32 v[218:219], v[26:27], v[40:41] op_sel_hi:[0,1]
	v_pk_mul_f32 v[226:227], v[26:27], v[40:41] op_sel:[1,0]
	ds_read_b128 v[4:7], v2 offset:6912
	v_pk_mul_f32 v[220:221], v[26:27], v[42:43] op_sel_hi:[0,1]
	v_pk_mul_f32 v[228:229], v[26:27], v[42:43] op_sel:[1,0]
	ds_read_b128 v[8:11], v2 offset:6928
	v_pk_mul_f32 v[222:223], v[26:27], v[44:45] op_sel_hi:[0,1]
	v_pk_mul_f32 v[230:231], v[26:27], v[44:45] op_sel:[1,0]
	ds_read_b128 v[208:211], v2 offset:18944
	v_pk_mul_f32 v[224:225], v[26:27], v[46:47] op_sel_hi:[0,1]
	v_pk_mul_f32 v[234:235], v[26:27], v[46:47] op_sel:[1,0]
	ds_read_b128 v[212:215], v2 offset:18960
	v_add_f32_e32 v172, v164, v165
	v_add_f32_e32 v174, v166, v167
	ds_read_b128 v[40:43], v2 offset:15104
	v_add_f32_e32 v160, v168, v169
	v_add_f32_e32 v161, v170, v171
	ds_read_b128 v[44:47], v2 offset:15120
	s_waitcnt lgkmcnt(15)
	v_pk_fma_f32 v[218:219], v[72:73], v[12:13], v[218:219]
	v_pk_fma_f32 v[226:227], v[80:81], v[12:13], v[226:227]
	ds_read_b64 v[26:27], v3 offset:43776
	v_pk_fma_f32 v[220:221], v[74:75], v[14:15], v[220:221]
	v_pk_fma_f32 v[228:229], v[82:83], v[14:15], v[228:229]
	v_add_f32_dpp v172, v172, v172 quad_perm:[1,0,3,2] row_mask:0xf bank_mask:0xf bound_ctrl:1
	v_add_f32_dpp v174, v174, v174 quad_perm:[1,0,3,2] row_mask:0xf bank_mask:0xf bound_ctrl:1
	v_add_f32_dpp v160, v160, v160 quad_perm:[1,0,3,2] row_mask:0xf bank_mask:0xf bound_ctrl:1
	v_add_f32_dpp v161, v161, v161 quad_perm:[1,0,3,2] row_mask:0xf bank_mask:0xf bound_ctrl:1
	s_waitcnt lgkmcnt(15)
	v_pk_fma_f32 v[222:223], v[76:77], v[28:29], v[222:223]
	v_pk_fma_f32 v[230:231], v[84:85], v[28:29], v[230:231]
	v_pk_fma_f32 v[224:225], v[78:79], v[30:31], v[224:225]
	v_pk_fma_f32 v[234:235], v[86:87], v[30:31], v[234:235]
	v_add_f32_dpp v172, v172, v172 quad_perm:[2,3,0,1] row_mask:0xf bank_mask:0xf bound_ctrl:1
	v_add_f32_dpp v174, v174, v174 quad_perm:[2,3,0,1] row_mask:0xf bank_mask:0xf bound_ctrl:1
	ds_read_b128 v[12:15], v2 offset:2816
	v_add_f32_dpp v160, v160, v160 quad_perm:[2,3,0,1] row_mask:0xf bank_mask:0xf bound_ctrl:1
	v_add_f32_dpp v161, v161, v161 quad_perm:[2,3,0,1] row_mask:0xf bank_mask:0xf bound_ctrl:1
	ds_read_b128 v[28:31], v2 offset:2832
	v_add_f32_dpp v172, v172, v172 row_half_mirror row_mask:0xf bank_mask:0xf bound_ctrl:1
	v_add_f32_dpp v174, v174, v174 row_half_mirror row_mask:0xf bank_mask:0xf bound_ctrl:1
	v_add_f32_dpp v160, v160, v160 row_half_mirror row_mask:0xf bank_mask:0xf bound_ctrl:1
	v_add_f32_dpp v161, v161, v161 row_half_mirror row_mask:0xf bank_mask:0xf bound_ctrl:1
	s_waitcnt lgkmcnt(15)
	v_pk_fma_f32 v[72:73], v[32:33], v[172:173], v[218:219] op_sel_hi:[1,0,1]
	v_pk_fma_f32 v[80:81], v[32:33], v[174:175], v[226:227] op_sel_hi:[1,0,1]
	v_pk_fma_f32 v[74:75], v[34:35], v[172:173], v[220:221] op_sel_hi:[1,0,1]
	v_pk_fma_f32 v[82:83], v[34:35], v[174:175], v[228:229] op_sel_hi:[1,0,1]
	s_waitcnt lgkmcnt(15)
	v_pk_fma_f32 v[76:77], v[36:37], v[172:173], v[222:223] op_sel_hi:[1,0,1]
	v_pk_fma_f32 v[84:85], v[36:37], v[174:175], v[230:231] op_sel_hi:[1,0,1]
	v_pk_fma_f32 v[78:79], v[38:39], v[172:173], v[224:225] op_sel_hi:[1,0,1]
	v_pk_fma_f32 v[86:87], v[38:39], v[174:175], v[234:235] op_sel_hi:[1,0,1]
	ds_read_b128 v[32:35], v2 offset:11008
	ds_read_b128 v[36:39], v2 offset:11024
	ds_write_b64 v1, v[160:161] offset:56064
	s_waitcnt lgkmcnt(15)
	v_pk_mul_f32 v[164:165], v[72:73], v[176:177]
	v_pk_mul_f32 v[166:167], v[80:81], v[176:177]
	s_waitcnt lgkmcnt(15)
	v_pk_mul_f32 v[168:169], v[72:73], v[48:49]
	v_pk_mul_f32 v[170:171], v[80:81], v[48:49]
	v_pk_fma_f32 v[164:165], v[74:75], v[178:179], v[164:165]
	v_pk_fma_f32 v[166:167], v[82:83], v[178:179], v[166:167]
	v_pk_fma_f32 v[168:169], v[74:75], v[50:51], v[168:169]
	v_pk_fma_f32 v[170:171], v[82:83], v[50:51], v[170:171]
	v_pk_fma_f32 v[164:165], v[76:77], v[180:181], v[164:165]
	v_pk_fma_f32 v[166:167], v[84:85], v[180:181], v[166:167]
	s_waitcnt lgkmcnt(15)
	v_pk_fma_f32 v[168:169], v[76:77], v[52:53], v[168:169]
	v_pk_fma_f32 v[170:171], v[84:85], v[52:53], v[170:171]
	v_pk_fma_f32 v[164:165], v[78:79], v[182:183], v[164:165]
	v_pk_fma_f32 v[166:167], v[86:87], v[182:183], v[166:167]
	v_pk_fma_f32 v[168:169], v[78:79], v[54:55], v[168:169]
	v_pk_fma_f32 v[170:171], v[86:87], v[54:55], v[170:171]
	s_waitcnt lgkmcnt(15)
	v_pk_mul_f32 v[218:219], v[216:217], v[200:201] op_sel_hi:[0,1]
	v_pk_mul_f32 v[226:227], v[216:217], v[200:201] op_sel:[1,0]
	ds_read_b128 v[176:179], v2 offset:7168
	v_pk_mul_f32 v[220:221], v[216:217], v[202:203] op_sel_hi:[0,1]
	v_pk_mul_f32 v[228:229], v[216:217], v[202:203] op_sel:[1,0]
	ds_read_b128 v[180:183], v2 offset:7184
	v_pk_mul_f32 v[222:223], v[216:217], v[204:205] op_sel_hi:[0,1]
	v_pk_mul_f32 v[230:231], v[216:217], v[204:205] op_sel:[1,0]
	ds_read_b128 v[48:51], v2 offset:19200
	v_pk_mul_f32 v[224:225], v[216:217], v[206:207] op_sel_hi:[0,1]
	v_pk_mul_f32 v[234:235], v[216:217], v[206:207] op_sel:[1,0]
	ds_read_b128 v[52:55], v2 offset:19216
	v_add_f32_e32 v172, v164, v165
	v_add_f32_e32 v174, v166, v167
	ds_read_b128 v[200:203], v2 offset:15360
	v_add_f32_e32 v160, v168, v169
	v_add_f32_e32 v161, v170, v171
	ds_read_b128 v[204:207], v2 offset:15376
	s_waitcnt lgkmcnt(15)
	v_pk_fma_f32 v[218:219], v[72:73], v[184:185], v[218:219]
	v_pk_fma_f32 v[226:227], v[80:81], v[184:185], v[226:227]
	ds_read_b64 v[216:217], v3 offset:44032
	v_pk_fma_f32 v[220:221], v[74:75], v[186:187], v[220:221]
	v_pk_fma_f32 v[228:229], v[82:83], v[186:187], v[228:229]
	v_add_f32_dpp v172, v172, v172 quad_perm:[1,0,3,2] row_mask:0xf bank_mask:0xf bound_ctrl:1
	v_add_f32_dpp v174, v174, v174 quad_perm:[1,0,3,2] row_mask:0xf bank_mask:0xf bound_ctrl:1
	v_add_f32_dpp v160, v160, v160 quad_perm:[1,0,3,2] row_mask:0xf bank_mask:0xf bound_ctrl:1
	v_add_f32_dpp v161, v161, v161 quad_perm:[1,0,3,2] row_mask:0xf bank_mask:0xf bound_ctrl:1
	s_waitcnt lgkmcnt(15)
	v_pk_fma_f32 v[222:223], v[76:77], v[188:189], v[222:223]
	v_pk_fma_f32 v[230:231], v[84:85], v[188:189], v[230:231]
	v_pk_fma_f32 v[224:225], v[78:79], v[190:191], v[224:225]
	v_pk_fma_f32 v[234:235], v[86:87], v[190:191], v[234:235]
	v_add_f32_dpp v172, v172, v172 quad_perm:[2,3,0,1] row_mask:0xf bank_mask:0xf bound_ctrl:1
	v_add_f32_dpp v174, v174, v174 quad_perm:[2,3,0,1] row_mask:0xf bank_mask:0xf bound_ctrl:1
	ds_read_b128 v[184:187], v2 offset:3072
	v_add_f32_dpp v160, v160, v160 quad_perm:[2,3,0,1] row_mask:0xf bank_mask:0xf bound_ctrl:1
	v_add_f32_dpp v161, v161, v161 quad_perm:[2,3,0,1] row_mask:0xf bank_mask:0xf bound_ctrl:1
	ds_read_b128 v[188:191], v2 offset:3088
	v_add_f32_dpp v172, v172, v172 row_half_mirror row_mask:0xf bank_mask:0xf bound_ctrl:1
	v_add_f32_dpp v174, v174, v174 row_half_mirror row_mask:0xf bank_mask:0xf bound_ctrl:1
	v_add_f32_dpp v160, v160, v160 row_half_mirror row_mask:0xf bank_mask:0xf bound_ctrl:1
	v_add_f32_dpp v161, v161, v161 row_half_mirror row_mask:0xf bank_mask:0xf bound_ctrl:1
	s_waitcnt lgkmcnt(15)
	v_pk_fma_f32 v[72:73], v[192:193], v[172:173], v[218:219] op_sel_hi:[1,0,1]
	v_pk_fma_f32 v[80:81], v[192:193], v[174:175], v[226:227] op_sel_hi:[1,0,1]
	v_pk_fma_f32 v[74:75], v[194:195], v[172:173], v[220:221] op_sel_hi:[1,0,1]
	v_pk_fma_f32 v[82:83], v[194:195], v[174:175], v[228:229] op_sel_hi:[1,0,1]
	s_waitcnt lgkmcnt(15)
	v_pk_fma_f32 v[76:77], v[196:197], v[172:173], v[222:223] op_sel_hi:[1,0,1]
	v_pk_fma_f32 v[84:85], v[196:197], v[174:175], v[230:231] op_sel_hi:[1,0,1]
	v_pk_fma_f32 v[78:79], v[198:199], v[172:173], v[224:225] op_sel_hi:[1,0,1]
	v_pk_fma_f32 v[86:87], v[198:199], v[174:175], v[234:235] op_sel_hi:[1,0,1]
	ds_read_b128 v[192:195], v2 offset:11264
	ds_read_b128 v[196:199], v2 offset:11280
	ds_write_b64 v1, v[160:161] offset:56320
	s_waitcnt lgkmcnt(15)
	v_pk_mul_f32 v[164:165], v[72:73], v[4:5]
	v_pk_mul_f32 v[166:167], v[80:81], v[4:5]
	s_waitcnt lgkmcnt(15)
	v_pk_mul_f32 v[168:169], v[72:73], v[208:209]
	v_pk_mul_f32 v[170:171], v[80:81], v[208:209]
	v_pk_fma_f32 v[164:165], v[74:75], v[6:7], v[164:165]
	v_pk_fma_f32 v[166:167], v[82:83], v[6:7], v[166:167]
	v_pk_fma_f32 v[168:169], v[74:75], v[210:211], v[168:169]
	v_pk_fma_f32 v[170:171], v[82:83], v[210:211], v[170:171]
	v_pk_fma_f32 v[164:165], v[76:77], v[8:9], v[164:165]
	v_pk_fma_f32 v[166:167], v[84:85], v[8:9], v[166:167]
	s_waitcnt lgkmcnt(15)
	v_pk_fma_f32 v[168:169], v[76:77], v[212:213], v[168:169]
	v_pk_fma_f32 v[170:171], v[84:85], v[212:213], v[170:171]
	v_pk_fma_f32 v[164:165], v[78:79], v[10:11], v[164:165]
	v_pk_fma_f32 v[166:167], v[86:87], v[10:11], v[166:167]
	v_pk_fma_f32 v[168:169], v[78:79], v[214:215], v[168:169]
	v_pk_fma_f32 v[170:171], v[86:87], v[214:215], v[170:171]
	s_waitcnt lgkmcnt(15)
	v_pk_mul_f32 v[218:219], v[26:27], v[40:41] op_sel_hi:[0,1]
	v_pk_mul_f32 v[226:227], v[26:27], v[40:41] op_sel:[1,0]
	ds_read_b128 v[4:7], v2 offset:7424
	v_pk_mul_f32 v[220:221], v[26:27], v[42:43] op_sel_hi:[0,1]
	v_pk_mul_f32 v[228:229], v[26:27], v[42:43] op_sel:[1,0]
	ds_read_b128 v[8:11], v2 offset:7440
	v_pk_mul_f32 v[222:223], v[26:27], v[44:45] op_sel_hi:[0,1]
	v_pk_mul_f32 v[230:231], v[26:27], v[44:45] op_sel:[1,0]
	ds_read_b128 v[208:211], v2 offset:19456
	v_pk_mul_f32 v[224:225], v[26:27], v[46:47] op_sel_hi:[0,1]
	v_pk_mul_f32 v[234:235], v[26:27], v[46:47] op_sel:[1,0]
	ds_read_b128 v[212:215], v2 offset:19472
	v_add_f32_e32 v172, v164, v165
	v_add_f32_e32 v174, v166, v167
	ds_read_b128 v[40:43], v2 offset:15616
	v_add_f32_e32 v160, v168, v169
	v_add_f32_e32 v161, v170, v171
	ds_read_b128 v[44:47], v2 offset:15632
	s_waitcnt lgkmcnt(15)
	v_pk_fma_f32 v[218:219], v[72:73], v[12:13], v[218:219]
	v_pk_fma_f32 v[226:227], v[80:81], v[12:13], v[226:227]
	ds_read_b64 v[26:27], v3 offset:44288
	v_pk_fma_f32 v[220:221], v[74:75], v[14:15], v[220:221]
	v_pk_fma_f32 v[228:229], v[82:83], v[14:15], v[228:229]
	v_add_f32_dpp v172, v172, v172 quad_perm:[1,0,3,2] row_mask:0xf bank_mask:0xf bound_ctrl:1
	v_add_f32_dpp v174, v174, v174 quad_perm:[1,0,3,2] row_mask:0xf bank_mask:0xf bound_ctrl:1
	v_add_f32_dpp v160, v160, v160 quad_perm:[1,0,3,2] row_mask:0xf bank_mask:0xf bound_ctrl:1
	v_add_f32_dpp v161, v161, v161 quad_perm:[1,0,3,2] row_mask:0xf bank_mask:0xf bound_ctrl:1
	s_waitcnt lgkmcnt(15)
	v_pk_fma_f32 v[222:223], v[76:77], v[28:29], v[222:223]
	v_pk_fma_f32 v[230:231], v[84:85], v[28:29], v[230:231]
	v_pk_fma_f32 v[224:225], v[78:79], v[30:31], v[224:225]
	v_pk_fma_f32 v[234:235], v[86:87], v[30:31], v[234:235]
	v_add_f32_dpp v172, v172, v172 quad_perm:[2,3,0,1] row_mask:0xf bank_mask:0xf bound_ctrl:1
	v_add_f32_dpp v174, v174, v174 quad_perm:[2,3,0,1] row_mask:0xf bank_mask:0xf bound_ctrl:1
	ds_read_b128 v[12:15], v2 offset:3328
	v_add_f32_dpp v160, v160, v160 quad_perm:[2,3,0,1] row_mask:0xf bank_mask:0xf bound_ctrl:1
	v_add_f32_dpp v161, v161, v161 quad_perm:[2,3,0,1] row_mask:0xf bank_mask:0xf bound_ctrl:1
	ds_read_b128 v[28:31], v2 offset:3344
	v_add_f32_dpp v172, v172, v172 row_half_mirror row_mask:0xf bank_mask:0xf bound_ctrl:1
	v_add_f32_dpp v174, v174, v174 row_half_mirror row_mask:0xf bank_mask:0xf bound_ctrl:1
	v_add_f32_dpp v160, v160, v160 row_half_mirror row_mask:0xf bank_mask:0xf bound_ctrl:1
	v_add_f32_dpp v161, v161, v161 row_half_mirror row_mask:0xf bank_mask:0xf bound_ctrl:1
	s_waitcnt lgkmcnt(15)
	v_pk_fma_f32 v[72:73], v[32:33], v[172:173], v[218:219] op_sel_hi:[1,0,1]
	v_pk_fma_f32 v[80:81], v[32:33], v[174:175], v[226:227] op_sel_hi:[1,0,1]
	v_pk_fma_f32 v[74:75], v[34:35], v[172:173], v[220:221] op_sel_hi:[1,0,1]
	v_pk_fma_f32 v[82:83], v[34:35], v[174:175], v[228:229] op_sel_hi:[1,0,1]
	s_waitcnt lgkmcnt(15)
	v_pk_fma_f32 v[76:77], v[36:37], v[172:173], v[222:223] op_sel_hi:[1,0,1]
	v_pk_fma_f32 v[84:85], v[36:37], v[174:175], v[230:231] op_sel_hi:[1,0,1]
	v_pk_fma_f32 v[78:79], v[38:39], v[172:173], v[224:225] op_sel_hi:[1,0,1]
	v_pk_fma_f32 v[86:87], v[38:39], v[174:175], v[234:235] op_sel_hi:[1,0,1]
	ds_read_b128 v[32:35], v2 offset:11520
	ds_read_b128 v[36:39], v2 offset:11536
	ds_write_b64 v1, v[160:161] offset:56576
	s_waitcnt lgkmcnt(15)
	v_pk_mul_f32 v[164:165], v[72:73], v[176:177]
	v_pk_mul_f32 v[166:167], v[80:81], v[176:177]
	s_waitcnt lgkmcnt(15)
	v_pk_mul_f32 v[168:169], v[72:73], v[48:49]
	v_pk_mul_f32 v[170:171], v[80:81], v[48:49]
	v_pk_fma_f32 v[164:165], v[74:75], v[178:179], v[164:165]
	v_pk_fma_f32 v[166:167], v[82:83], v[178:179], v[166:167]
	v_pk_fma_f32 v[168:169], v[74:75], v[50:51], v[168:169]
	v_pk_fma_f32 v[170:171], v[82:83], v[50:51], v[170:171]
	v_pk_fma_f32 v[164:165], v[76:77], v[180:181], v[164:165]
	v_pk_fma_f32 v[166:167], v[84:85], v[180:181], v[166:167]
	s_waitcnt lgkmcnt(15)
	v_pk_fma_f32 v[168:169], v[76:77], v[52:53], v[168:169]
	v_pk_fma_f32 v[170:171], v[84:85], v[52:53], v[170:171]
	v_pk_fma_f32 v[164:165], v[78:79], v[182:183], v[164:165]
	v_pk_fma_f32 v[166:167], v[86:87], v[182:183], v[166:167]
	v_pk_fma_f32 v[168:169], v[78:79], v[54:55], v[168:169]
	v_pk_fma_f32 v[170:171], v[86:87], v[54:55], v[170:171]
	s_waitcnt lgkmcnt(15)
	v_pk_mul_f32 v[218:219], v[216:217], v[200:201] op_sel_hi:[0,1]
	v_pk_mul_f32 v[226:227], v[216:217], v[200:201] op_sel:[1,0]
	ds_read_b128 v[176:179], v2 offset:7680
	v_pk_mul_f32 v[220:221], v[216:217], v[202:203] op_sel_hi:[0,1]
	v_pk_mul_f32 v[228:229], v[216:217], v[202:203] op_sel:[1,0]
	ds_read_b128 v[180:183], v2 offset:7696
	v_pk_mul_f32 v[222:223], v[216:217], v[204:205] op_sel_hi:[0,1]
	v_pk_mul_f32 v[230:231], v[216:217], v[204:205] op_sel:[1,0]
	ds_read_b128 v[48:51], v2 offset:19712
	v_pk_mul_f32 v[224:225], v[216:217], v[206:207] op_sel_hi:[0,1]
	v_pk_mul_f32 v[234:235], v[216:217], v[206:207] op_sel:[1,0]
	ds_read_b128 v[52:55], v2 offset:19728
	v_add_f32_e32 v172, v164, v165
	v_add_f32_e32 v174, v166, v167
	ds_read_b128 v[200:203], v2 offset:15872
	v_add_f32_e32 v160, v168, v169
	v_add_f32_e32 v161, v170, v171
	ds_read_b128 v[204:207], v2 offset:15888
	s_waitcnt lgkmcnt(15)
	v_pk_fma_f32 v[218:219], v[72:73], v[184:185], v[218:219]
	v_pk_fma_f32 v[226:227], v[80:81], v[184:185], v[226:227]
	ds_read_b64 v[216:217], v3 offset:44544
	v_pk_fma_f32 v[220:221], v[74:75], v[186:187], v[220:221]
	v_pk_fma_f32 v[228:229], v[82:83], v[186:187], v[228:229]
	v_add_f32_dpp v172, v172, v172 quad_perm:[1,0,3,2] row_mask:0xf bank_mask:0xf bound_ctrl:1
	v_add_f32_dpp v174, v174, v174 quad_perm:[1,0,3,2] row_mask:0xf bank_mask:0xf bound_ctrl:1
	v_add_f32_dpp v160, v160, v160 quad_perm:[1,0,3,2] row_mask:0xf bank_mask:0xf bound_ctrl:1
	v_add_f32_dpp v161, v161, v161 quad_perm:[1,0,3,2] row_mask:0xf bank_mask:0xf bound_ctrl:1
	s_waitcnt lgkmcnt(15)
	v_pk_fma_f32 v[222:223], v[76:77], v[188:189], v[222:223]
	v_pk_fma_f32 v[230:231], v[84:85], v[188:189], v[230:231]
	v_pk_fma_f32 v[224:225], v[78:79], v[190:191], v[224:225]
	v_pk_fma_f32 v[234:235], v[86:87], v[190:191], v[234:235]
	v_add_f32_dpp v172, v172, v172 quad_perm:[2,3,0,1] row_mask:0xf bank_mask:0xf bound_ctrl:1
	v_add_f32_dpp v174, v174, v174 quad_perm:[2,3,0,1] row_mask:0xf bank_mask:0xf bound_ctrl:1
	ds_read_b128 v[184:187], v2 offset:3584
	v_add_f32_dpp v160, v160, v160 quad_perm:[2,3,0,1] row_mask:0xf bank_mask:0xf bound_ctrl:1
	v_add_f32_dpp v161, v161, v161 quad_perm:[2,3,0,1] row_mask:0xf bank_mask:0xf bound_ctrl:1
	ds_read_b128 v[188:191], v2 offset:3600
	v_add_f32_dpp v172, v172, v172 row_half_mirror row_mask:0xf bank_mask:0xf bound_ctrl:1
	v_add_f32_dpp v174, v174, v174 row_half_mirror row_mask:0xf bank_mask:0xf bound_ctrl:1
	v_add_f32_dpp v160, v160, v160 row_half_mirror row_mask:0xf bank_mask:0xf bound_ctrl:1
	v_add_f32_dpp v161, v161, v161 row_half_mirror row_mask:0xf bank_mask:0xf bound_ctrl:1
	s_waitcnt lgkmcnt(15)
	v_pk_fma_f32 v[72:73], v[192:193], v[172:173], v[218:219] op_sel_hi:[1,0,1]
	v_pk_fma_f32 v[80:81], v[192:193], v[174:175], v[226:227] op_sel_hi:[1,0,1]
	v_pk_fma_f32 v[74:75], v[194:195], v[172:173], v[220:221] op_sel_hi:[1,0,1]
	v_pk_fma_f32 v[82:83], v[194:195], v[174:175], v[228:229] op_sel_hi:[1,0,1]
	s_waitcnt lgkmcnt(15)
	v_pk_fma_f32 v[76:77], v[196:197], v[172:173], v[222:223] op_sel_hi:[1,0,1]
	v_pk_fma_f32 v[84:85], v[196:197], v[174:175], v[230:231] op_sel_hi:[1,0,1]
	v_pk_fma_f32 v[78:79], v[198:199], v[172:173], v[224:225] op_sel_hi:[1,0,1]
	v_pk_fma_f32 v[86:87], v[198:199], v[174:175], v[234:235] op_sel_hi:[1,0,1]
	ds_read_b128 v[192:195], v2 offset:11776
	ds_read_b128 v[196:199], v2 offset:11792
	ds_write_b64 v1, v[160:161] offset:56832
	s_waitcnt lgkmcnt(15)
	v_pk_mul_f32 v[164:165], v[72:73], v[4:5]
	v_pk_mul_f32 v[166:167], v[80:81], v[4:5]
	s_waitcnt lgkmcnt(15)
	v_pk_mul_f32 v[168:169], v[72:73], v[208:209]
	v_pk_mul_f32 v[170:171], v[80:81], v[208:209]
	v_pk_fma_f32 v[164:165], v[74:75], v[6:7], v[164:165]
	v_pk_fma_f32 v[166:167], v[82:83], v[6:7], v[166:167]
	v_pk_fma_f32 v[168:169], v[74:75], v[210:211], v[168:169]
	v_pk_fma_f32 v[170:171], v[82:83], v[210:211], v[170:171]
	v_pk_fma_f32 v[164:165], v[76:77], v[8:9], v[164:165]
	v_pk_fma_f32 v[166:167], v[84:85], v[8:9], v[166:167]
	s_waitcnt lgkmcnt(15)
	v_pk_fma_f32 v[168:169], v[76:77], v[212:213], v[168:169]
	v_pk_fma_f32 v[170:171], v[84:85], v[212:213], v[170:171]
	v_pk_fma_f32 v[164:165], v[78:79], v[10:11], v[164:165]
	v_pk_fma_f32 v[166:167], v[86:87], v[10:11], v[166:167]
	v_pk_fma_f32 v[168:169], v[78:79], v[214:215], v[168:169]
	v_pk_fma_f32 v[170:171], v[86:87], v[214:215], v[170:171]
	s_waitcnt lgkmcnt(15)
	v_pk_mul_f32 v[218:219], v[26:27], v[40:41] op_sel_hi:[0,1]
	v_pk_mul_f32 v[226:227], v[26:27], v[40:41] op_sel:[1,0]
	ds_read_b128 v[4:7], v2 offset:7936
	v_pk_mul_f32 v[220:221], v[26:27], v[42:43] op_sel_hi:[0,1]
	v_pk_mul_f32 v[228:229], v[26:27], v[42:43] op_sel:[1,0]
	ds_read_b128 v[8:11], v2 offset:7952
	v_pk_mul_f32 v[222:223], v[26:27], v[44:45] op_sel_hi:[0,1]
	v_pk_mul_f32 v[230:231], v[26:27], v[44:45] op_sel:[1,0]
	ds_read_b128 v[208:211], v2 offset:19968
	v_pk_mul_f32 v[224:225], v[26:27], v[46:47] op_sel_hi:[0,1]
	v_pk_mul_f32 v[234:235], v[26:27], v[46:47] op_sel:[1,0]
	ds_read_b128 v[212:215], v2 offset:19984
	v_add_f32_e32 v172, v164, v165
	v_add_f32_e32 v174, v166, v167
	ds_read_b128 v[40:43], v2 offset:16128
	v_add_f32_e32 v160, v168, v169
	v_add_f32_e32 v161, v170, v171
	ds_read_b128 v[44:47], v2 offset:16144
	s_waitcnt lgkmcnt(15)
	v_pk_fma_f32 v[218:219], v[72:73], v[12:13], v[218:219]
	v_pk_fma_f32 v[226:227], v[80:81], v[12:13], v[226:227]
	ds_read_b64 v[26:27], v3 offset:44800
	v_pk_fma_f32 v[220:221], v[74:75], v[14:15], v[220:221]
	v_pk_fma_f32 v[228:229], v[82:83], v[14:15], v[228:229]
	v_add_f32_dpp v172, v172, v172 quad_perm:[1,0,3,2] row_mask:0xf bank_mask:0xf bound_ctrl:1
	v_add_f32_dpp v174, v174, v174 quad_perm:[1,0,3,2] row_mask:0xf bank_mask:0xf bound_ctrl:1
	v_add_f32_dpp v160, v160, v160 quad_perm:[1,0,3,2] row_mask:0xf bank_mask:0xf bound_ctrl:1
	v_add_f32_dpp v161, v161, v161 quad_perm:[1,0,3,2] row_mask:0xf bank_mask:0xf bound_ctrl:1
	s_waitcnt lgkmcnt(15)
	v_pk_fma_f32 v[222:223], v[76:77], v[28:29], v[222:223]
	v_pk_fma_f32 v[230:231], v[84:85], v[28:29], v[230:231]
	v_pk_fma_f32 v[224:225], v[78:79], v[30:31], v[224:225]
	v_pk_fma_f32 v[234:235], v[86:87], v[30:31], v[234:235]
	v_add_f32_dpp v172, v172, v172 quad_perm:[2,3,0,1] row_mask:0xf bank_mask:0xf bound_ctrl:1
	v_add_f32_dpp v174, v174, v174 quad_perm:[2,3,0,1] row_mask:0xf bank_mask:0xf bound_ctrl:1
	ds_read_b128 v[12:15], v2 offset:3840
	v_add_f32_dpp v160, v160, v160 quad_perm:[2,3,0,1] row_mask:0xf bank_mask:0xf bound_ctrl:1
	v_add_f32_dpp v161, v161, v161 quad_perm:[2,3,0,1] row_mask:0xf bank_mask:0xf bound_ctrl:1
	ds_read_b128 v[28:31], v2 offset:3856
	v_add_f32_dpp v172, v172, v172 row_half_mirror row_mask:0xf bank_mask:0xf bound_ctrl:1
	v_add_f32_dpp v174, v174, v174 row_half_mirror row_mask:0xf bank_mask:0xf bound_ctrl:1
	v_add_f32_dpp v160, v160, v160 row_half_mirror row_mask:0xf bank_mask:0xf bound_ctrl:1
	v_add_f32_dpp v161, v161, v161 row_half_mirror row_mask:0xf bank_mask:0xf bound_ctrl:1
	s_waitcnt lgkmcnt(15)
	v_pk_fma_f32 v[72:73], v[32:33], v[172:173], v[218:219] op_sel_hi:[1,0,1]
	v_pk_fma_f32 v[80:81], v[32:33], v[174:175], v[226:227] op_sel_hi:[1,0,1]
	v_pk_fma_f32 v[74:75], v[34:35], v[172:173], v[220:221] op_sel_hi:[1,0,1]
	v_pk_fma_f32 v[82:83], v[34:35], v[174:175], v[228:229] op_sel_hi:[1,0,1]
	s_waitcnt lgkmcnt(15)
	v_pk_fma_f32 v[76:77], v[36:37], v[172:173], v[222:223] op_sel_hi:[1,0,1]
	v_pk_fma_f32 v[84:85], v[36:37], v[174:175], v[230:231] op_sel_hi:[1,0,1]
	v_pk_fma_f32 v[78:79], v[38:39], v[172:173], v[224:225] op_sel_hi:[1,0,1]
	v_pk_fma_f32 v[86:87], v[38:39], v[174:175], v[234:235] op_sel_hi:[1,0,1]
	ds_read_b128 v[32:35], v2 offset:12032
	ds_read_b128 v[36:39], v2 offset:12048
	ds_write_b64 v1, v[160:161] offset:57088
	s_waitcnt lgkmcnt(15)
	v_pk_mul_f32 v[164:165], v[72:73], v[176:177]
	v_pk_mul_f32 v[166:167], v[80:81], v[176:177]
	s_waitcnt lgkmcnt(15)
	v_pk_mul_f32 v[168:169], v[72:73], v[48:49]
	v_pk_mul_f32 v[170:171], v[80:81], v[48:49]
	v_pk_fma_f32 v[164:165], v[74:75], v[178:179], v[164:165]
	v_pk_fma_f32 v[166:167], v[82:83], v[178:179], v[166:167]
	v_pk_fma_f32 v[168:169], v[74:75], v[50:51], v[168:169]
	v_pk_fma_f32 v[170:171], v[82:83], v[50:51], v[170:171]
	v_pk_fma_f32 v[164:165], v[76:77], v[180:181], v[164:165]
	v_pk_fma_f32 v[166:167], v[84:85], v[180:181], v[166:167]
	s_waitcnt lgkmcnt(15)
	v_pk_fma_f32 v[168:169], v[76:77], v[52:53], v[168:169]
	v_pk_fma_f32 v[170:171], v[84:85], v[52:53], v[170:171]
	v_pk_fma_f32 v[164:165], v[78:79], v[182:183], v[164:165]
	v_pk_fma_f32 v[166:167], v[86:87], v[182:183], v[166:167]
	v_pk_fma_f32 v[168:169], v[78:79], v[54:55], v[168:169]
	v_pk_fma_f32 v[170:171], v[86:87], v[54:55], v[170:171]
	s_waitcnt lgkmcnt(15)
	v_pk_mul_f32 v[218:219], v[216:217], v[200:201] op_sel_hi:[0,1]
	v_pk_mul_f32 v[226:227], v[216:217], v[200:201] op_sel:[1,0]
	ds_read_b128 v[48:51], v2 offset:20224
	v_pk_mul_f32 v[220:221], v[216:217], v[202:203] op_sel_hi:[0,1]
	v_pk_mul_f32 v[228:229], v[216:217], v[202:203] op_sel:[1,0]
	ds_read_b128 v[52:55], v2 offset:20240
	v_pk_mul_f32 v[222:223], v[216:217], v[204:205] op_sel_hi:[0,1]
	v_pk_mul_f32 v[230:231], v[216:217], v[204:205] op_sel:[1,0]
	v_pk_mul_f32 v[224:225], v[216:217], v[206:207] op_sel_hi:[0,1]
	v_pk_mul_f32 v[234:235], v[216:217], v[206:207] op_sel:[1,0]
	v_add_f32_e32 v172, v164, v165
	v_add_f32_e32 v174, v166, v167
	v_add_f32_e32 v160, v168, v169
	v_add_f32_e32 v161, v170, v171
	s_waitcnt lgkmcnt(15)
	v_pk_fma_f32 v[218:219], v[72:73], v[184:185], v[218:219]
	v_pk_fma_f32 v[226:227], v[80:81], v[184:185], v[226:227]
	v_pk_fma_f32 v[220:221], v[74:75], v[186:187], v[220:221]
	v_pk_fma_f32 v[228:229], v[82:83], v[186:187], v[228:229]
	v_add_f32_dpp v172, v172, v172 quad_perm:[1,0,3,2] row_mask:0xf bank_mask:0xf bound_ctrl:1
	v_add_f32_dpp v174, v174, v174 quad_perm:[1,0,3,2] row_mask:0xf bank_mask:0xf bound_ctrl:1
	v_add_f32_dpp v160, v160, v160 quad_perm:[1,0,3,2] row_mask:0xf bank_mask:0xf bound_ctrl:1
	v_add_f32_dpp v161, v161, v161 quad_perm:[1,0,3,2] row_mask:0xf bank_mask:0xf bound_ctrl:1
	s_waitcnt lgkmcnt(15)
	v_pk_fma_f32 v[222:223], v[76:77], v[188:189], v[222:223]
	v_pk_fma_f32 v[230:231], v[84:85], v[188:189], v[230:231]
	v_pk_fma_f32 v[224:225], v[78:79], v[190:191], v[224:225]
	v_pk_fma_f32 v[234:235], v[86:87], v[190:191], v[234:235]
	v_add_f32_dpp v172, v172, v172 quad_perm:[2,3,0,1] row_mask:0xf bank_mask:0xf bound_ctrl:1
	v_add_f32_dpp v174, v174, v174 quad_perm:[2,3,0,1] row_mask:0xf bank_mask:0xf bound_ctrl:1
	v_add_f32_dpp v160, v160, v160 quad_perm:[2,3,0,1] row_mask:0xf bank_mask:0xf bound_ctrl:1
	v_add_f32_dpp v161, v161, v161 quad_perm:[2,3,0,1] row_mask:0xf bank_mask:0xf bound_ctrl:1
	v_add_f32_dpp v172, v172, v172 row_half_mirror row_mask:0xf bank_mask:0xf bound_ctrl:1
	v_add_f32_dpp v174, v174, v174 row_half_mirror row_mask:0xf bank_mask:0xf bound_ctrl:1
	v_add_f32_dpp v160, v160, v160 row_half_mirror row_mask:0xf bank_mask:0xf bound_ctrl:1
	v_add_f32_dpp v161, v161, v161 row_half_mirror row_mask:0xf bank_mask:0xf bound_ctrl:1
	s_waitcnt lgkmcnt(15)
	v_pk_fma_f32 v[72:73], v[192:193], v[172:173], v[218:219] op_sel_hi:[1,0,1]
	v_pk_fma_f32 v[80:81], v[192:193], v[174:175], v[226:227] op_sel_hi:[1,0,1]
	v_pk_fma_f32 v[74:75], v[194:195], v[172:173], v[220:221] op_sel_hi:[1,0,1]
	v_pk_fma_f32 v[82:83], v[194:195], v[174:175], v[228:229] op_sel_hi:[1,0,1]
	s_waitcnt lgkmcnt(15)
	v_pk_fma_f32 v[76:77], v[196:197], v[172:173], v[222:223] op_sel_hi:[1,0,1]
	v_pk_fma_f32 v[84:85], v[196:197], v[174:175], v[230:231] op_sel_hi:[1,0,1]
	v_pk_fma_f32 v[78:79], v[198:199], v[172:173], v[224:225] op_sel_hi:[1,0,1]
	v_pk_fma_f32 v[86:87], v[198:199], v[174:175], v[234:235] op_sel_hi:[1,0,1]
	ds_write_b64 v1, v[160:161] offset:57344
	s_waitcnt lgkmcnt(14)
	v_pk_mul_f32 v[164:165], v[72:73], v[4:5]
	v_pk_mul_f32 v[166:167], v[80:81], v[4:5]
	s_waitcnt lgkmcnt(12)
	v_pk_mul_f32 v[168:169], v[72:73], v[208:209]
	v_pk_mul_f32 v[170:171], v[80:81], v[208:209]
	v_pk_fma_f32 v[164:165], v[74:75], v[6:7], v[164:165]
	v_pk_fma_f32 v[166:167], v[82:83], v[6:7], v[166:167]
	v_pk_fma_f32 v[168:169], v[74:75], v[210:211], v[168:169]
	v_pk_fma_f32 v[170:171], v[82:83], v[210:211], v[170:171]
	v_pk_fma_f32 v[164:165], v[76:77], v[8:9], v[164:165]
	v_pk_fma_f32 v[166:167], v[84:85], v[8:9], v[166:167]
	s_waitcnt lgkmcnt(11)
	v_pk_fma_f32 v[168:169], v[76:77], v[212:213], v[168:169]
	v_pk_fma_f32 v[170:171], v[84:85], v[212:213], v[170:171]
	v_pk_fma_f32 v[164:165], v[78:79], v[10:11], v[164:165]
	v_pk_fma_f32 v[166:167], v[86:87], v[10:11], v[166:167]
	v_pk_fma_f32 v[168:169], v[78:79], v[214:215], v[168:169]
	v_pk_fma_f32 v[170:171], v[86:87], v[214:215], v[170:171]
	s_waitcnt lgkmcnt(8)
	v_pk_mul_f32 v[218:219], v[26:27], v[40:41] op_sel_hi:[0,1]
	v_pk_mul_f32 v[226:227], v[26:27], v[40:41] op_sel:[1,0]
	v_pk_mul_f32 v[220:221], v[26:27], v[42:43] op_sel_hi:[0,1]
	v_pk_mul_f32 v[228:229], v[26:27], v[42:43] op_sel:[1,0]
	v_pk_mul_f32 v[222:223], v[26:27], v[44:45] op_sel_hi:[0,1]
	v_pk_mul_f32 v[230:231], v[26:27], v[44:45] op_sel:[1,0]
	v_pk_mul_f32 v[224:225], v[26:27], v[46:47] op_sel_hi:[0,1]
	v_pk_mul_f32 v[234:235], v[26:27], v[46:47] op_sel:[1,0]
	v_add_f32_e32 v172, v164, v165
	v_add_f32_e32 v174, v166, v167
	v_add_f32_e32 v160, v168, v169
	v_add_f32_e32 v161, v170, v171
	s_waitcnt lgkmcnt(7)
	v_pk_fma_f32 v[218:219], v[72:73], v[12:13], v[218:219]
	v_pk_fma_f32 v[226:227], v[80:81], v[12:13], v[226:227]
	v_pk_fma_f32 v[220:221], v[74:75], v[14:15], v[220:221]
	v_pk_fma_f32 v[228:229], v[82:83], v[14:15], v[228:229]
	v_add_f32_dpp v172, v172, v172 quad_perm:[1,0,3,2] row_mask:0xf bank_mask:0xf bound_ctrl:1
	v_add_f32_dpp v174, v174, v174 quad_perm:[1,0,3,2] row_mask:0xf bank_mask:0xf bound_ctrl:1
	v_add_f32_dpp v160, v160, v160 quad_perm:[1,0,3,2] row_mask:0xf bank_mask:0xf bound_ctrl:1
	v_add_f32_dpp v161, v161, v161 quad_perm:[1,0,3,2] row_mask:0xf bank_mask:0xf bound_ctrl:1
	s_waitcnt lgkmcnt(6)
	v_pk_fma_f32 v[222:223], v[76:77], v[28:29], v[222:223]
	v_pk_fma_f32 v[230:231], v[84:85], v[28:29], v[230:231]
	v_pk_fma_f32 v[224:225], v[78:79], v[30:31], v[224:225]
	v_pk_fma_f32 v[234:235], v[86:87], v[30:31], v[234:235]
	v_add_f32_dpp v172, v172, v172 quad_perm:[2,3,0,1] row_mask:0xf bank_mask:0xf bound_ctrl:1
	v_add_f32_dpp v174, v174, v174 quad_perm:[2,3,0,1] row_mask:0xf bank_mask:0xf bound_ctrl:1
	v_add_f32_dpp v160, v160, v160 quad_perm:[2,3,0,1] row_mask:0xf bank_mask:0xf bound_ctrl:1
	v_add_f32_dpp v161, v161, v161 quad_perm:[2,3,0,1] row_mask:0xf bank_mask:0xf bound_ctrl:1
	v_add_f32_dpp v172, v172, v172 row_half_mirror row_mask:0xf bank_mask:0xf bound_ctrl:1
	v_add_f32_dpp v174, v174, v174 row_half_mirror row_mask:0xf bank_mask:0xf bound_ctrl:1
	v_add_f32_dpp v160, v160, v160 row_half_mirror row_mask:0xf bank_mask:0xf bound_ctrl:1
	v_add_f32_dpp v161, v161, v161 row_half_mirror row_mask:0xf bank_mask:0xf bound_ctrl:1
	s_waitcnt lgkmcnt(5)
	v_pk_fma_f32 v[72:73], v[32:33], v[172:173], v[218:219] op_sel_hi:[1,0,1]
	v_pk_fma_f32 v[80:81], v[32:33], v[174:175], v[226:227] op_sel_hi:[1,0,1]
	v_pk_fma_f32 v[74:75], v[34:35], v[172:173], v[220:221] op_sel_hi:[1,0,1]
	v_pk_fma_f32 v[82:83], v[34:35], v[174:175], v[228:229] op_sel_hi:[1,0,1]
	s_waitcnt lgkmcnt(4)
	v_pk_fma_f32 v[76:77], v[36:37], v[172:173], v[222:223] op_sel_hi:[1,0,1]
	v_pk_fma_f32 v[84:85], v[36:37], v[174:175], v[230:231] op_sel_hi:[1,0,1]
	v_pk_fma_f32 v[78:79], v[38:39], v[172:173], v[224:225] op_sel_hi:[1,0,1]
	v_pk_fma_f32 v[86:87], v[38:39], v[174:175], v[234:235] op_sel_hi:[1,0,1]
	ds_write_b64 v1, v[160:161] offset:57600
	s_waitcnt lgkmcnt(3)
	v_pk_mul_f32 v[168:169], v[72:73], v[48:49]
	v_pk_mul_f32 v[170:171], v[80:81], v[48:49]
	v_pk_fma_f32 v[168:169], v[74:75], v[50:51], v[168:169]
	v_pk_fma_f32 v[170:171], v[82:83], v[50:51], v[170:171]
	s_waitcnt lgkmcnt(2)
	v_pk_fma_f32 v[168:169], v[76:77], v[52:53], v[168:169]
	v_pk_fma_f32 v[170:171], v[84:85], v[52:53], v[170:171]
	v_pk_fma_f32 v[168:169], v[78:79], v[54:55], v[168:169]
	v_pk_fma_f32 v[170:171], v[86:87], v[54:55], v[170:171]
	v_add_f32_e32 v160, v168, v169
	v_add_f32_e32 v161, v170, v171
	s_nop 0
	v_add_f32_dpp v160, v160, v160 quad_perm:[1,0,3,2] row_mask:0xf bank_mask:0xf bound_ctrl:1
	v_add_f32_dpp v161, v161, v161 quad_perm:[1,0,3,2] row_mask:0xf bank_mask:0xf bound_ctrl:1
	s_nop 0
	v_add_f32_dpp v160, v160, v160 quad_perm:[2,3,0,1] row_mask:0xf bank_mask:0xf bound_ctrl:1
	v_add_f32_dpp v161, v161, v161 quad_perm:[2,3,0,1] row_mask:0xf bank_mask:0xf bound_ctrl:1
	s_nop 0
	v_add_f32_dpp v160, v160, v160 row_half_mirror row_mask:0xf bank_mask:0xf bound_ctrl:1
	v_add_f32_dpp v161, v161, v161 row_half_mirror row_mask:0xf bank_mask:0xf bound_ctrl:1
	ds_write_b64 v1, v[160:161] offset:57856
	s_add_i32 s3, s2, 1
	s_mov_b64 s[36:37], 0
